# attention key-pair loop LDS reads software-pipelined over 7 buffers; prompt S5 step rewritten with packed f32 FMA chains and per-block u unpack; skip-term loads hoisted
# speedup vs baseline: 1.0383x; 1.0383x over previous
; __device__ __forceinline__ unsigned pk2(float lo, float hi) { unsigned r; asm volatile("v_cvt_pk_bf16_f32 %0, %1, %2" : "=v"(r) : "v"(lo), "v"(hi)); return r; }
; __device__ __forceinline__ void s5_item(CPar p, int l, int s, int g, float* wl) {
;     ...
;     const float mag = expf(lr * step), ab_re = mag * cs, ab_im = mag * sn;
;     const float den = lr * lr + li * li, nr = ab_re - 1.f, f_re = (nr * lr + ab_im * li) / den, f_im = (ab_im * lr - nr * li) / den;
;     float bbr[16], bbi[16];
; #pragma unroll
;     for (int hh = 0; hh < 16; ++hh) { const float br = p->in[I_BRE][(size_t)gp * 16 + hh], bi = p->in[I_BIM][(size_t)gp * 16 + hh]; bbr[hh] = f_re * br - f_im * bi; bbi[hh] = f_re * bi + f_im * br; }
;     bf16x8 cfrag[4];
; #pragma unroll
;     for (int ks = 0; ks < 4; ++ks) { const int k0 = ks * 32 + fq * 8; const bool im = k0 >= 64;
;         const float* cp = (im ? p->in[I_CIM] : p->in[I_CRE]) + ((size_t)(l * 32 + g) * 16 + fr) * 64 + (k0 & 63);
;         const f32x4 c0 = *(const f32x4*)cp, c1 = *(const f32x4*)(cp + 4); const float sg = im ? -1.f : 1.f;
;         u32x4 w; w[0] = pk2(sg * c0[0], sg * c0[1]); w[1] = pk2(sg * c0[2], sg * c0[3]); w[2] = pk2(sg * c1[0], sg * c1[1]); w[3] = pk2(sg * c1[2], sg * c1[3]);
;         cfrag[ks] = __builtin_bit_cast(bf16x8, w); }
;     float xr = prompt ? 0.f : p->in[I_S5R][(size_t)(l * 16 + b) * 2048 + g * 64 + lane], xi = prompt ? 0.f : p->in[I_S5I][(size_t)(l * 16 + b) * 2048 + g * 64 + lane];
;     const float dsk = p->in[I_DS5][(size_t)(l * 32 + g) * 16 + fr];
;     u32x4 ua = {0, 0, 0, 0}, ub = {0, 0, 0, 0};
;     { const int r0 = row_of(s, 0); if (lane < 16) { const u32x4* up = (const u32x4*)(U + (size_t)(r0 + lane) * 512 + g * 16); ua = up[0]; ub = up[1]; } }
.LBB0_679:
	s_or_b64 exec, exec, s[26:27]
	v_mul_f32_e32 v2, v62, v64
	v_mul_f32_e32 v3, 0x3fb8aa3b, v2
	s_mov_b32 s6, 0x3fb8aa3b
	v_fma_f32 v61, v2, s6, -v3
	v_rndne_f32_e32 v64, v3
	v_fmac_f32_e32 v61, 0x32a5705f, v2
	v_sub_f32_e32 v3, v3, v64
	v_add_f32_e32 v3, v3, v61
	v_exp_f32_e32 v3, v3
	v_cvt_i32_f32_e32 v61, v64
	s_mov_b32 s6, 0xc2ce8ed0
	v_cmp_ngt_f32_e32 vcc, s6, v2
	s_mov_b32 s6, 0x42b17218
	v_ldexp_f32 v3, v3, v61
	v_cndmask_b32_e32 v3, 0, v3, vcc
	v_cmp_nlt_f32_e32 vcc, s6, v2
	v_mov_b32_e32 v64, v63
	v_pk_mul_f32 v[66:67], v[62:63], v[62:63]
	v_cndmask_b32_e32 v3, v206, v3, vcc
	v_mul_f32_e32 v60, v3, v60
	v_fma_f32 v61, v3, v65, -1.0
	v_mul_f32_e32 v2, v3, v65
	v_pk_mul_f32 v[64:65], v[64:65], v[60:61] op_sel:[0,1] op_sel_hi:[0,0]
	v_pk_fma_f32 v[68:69], v[62:63], v[60:61], v[64:65] neg_lo:[0,0,1] neg_hi:[0,0,1]
	v_pk_fma_f32 v[62:63], v[62:63], v[60:61], v[64:65] op_sel_hi:[0,1,1]
	v_pk_add_f32 v[64:65], v[66:67], v[66:67] op_sel:[0,1] op_sel_hi:[0,1]
	v_div_scale_f32 v3, s[6:7], v65, v65, v63
	v_rcp_f32_e32 v61, v3
	v_lshlrev_b32_e32 v1, 3, v104
	v_mov_b32_e32 v106, 0
	v_lshlrev_b32_e32 v1, 1, v1
	v_fma_f32 v62, -v3, v61, 1.0
	v_fmac_f32_e32 v61, v62, v61
	v_div_scale_f32 v62, vcc, v63, v65, v63
	v_mul_f32_e32 v66, v62, v61
	v_fma_f32 v67, -v3, v66, v62
	v_fmac_f32_e32 v66, v67, v61
	v_fma_f32 v3, -v3, v66, v62
	v_div_fmas_f32 v3, v3, v61, v66
	v_div_fixup_f32 v101, v3, v65, v63
	v_div_scale_f32 v3, s[6:7], v64, v64, v68
	v_rcp_f32_e32 v61, v3
	s_lshl_b32 s11, s9, 11
	s_mov_b32 s12, 0
	v_mov_b32_e32 v107, v106
	v_fma_f32 v62, -v3, v61, 1.0
	v_fmac_f32_e32 v61, v62, v61
	v_div_scale_f32 v62, vcc, v68, v64, v68
	v_mul_f32_e32 v63, v62, v61
	v_fma_f32 v65, -v3, v63, v62
	v_fmac_f32_e32 v63, v65, v61
	v_fma_f32 v3, -v3, v63, v62
	v_div_fmas_f32 v3, v3, v61, v63
	v_div_fixup_f32 v100, v3, v64, v68
	v_pk_mul_f32 v[66:67], v[56:57], v[100:101]
	v_pk_mul_f32 v[62:63], v[100:101], v[56:57] op_sel:[1,0] op_sel_hi:[0,1]
	v_pk_fma_f32 v[56:57], v[100:101], v[52:53], v[62:63] neg_lo:[0,0,1] neg_hi:[0,0,1]
	v_pk_fma_f32 v[62:63], v[100:101], v[52:53], v[62:63]
	v_pk_fma_f32 v[64:65], v[52:53], v[100:101], v[66:67] op_sel:[1,0,1] op_sel_hi:[0,1,0] neg_lo:[0,0,1] neg_hi:[0,0,1]
	v_pk_fma_f32 v[52:53], v[52:53], v[100:101], v[66:67] op_sel:[1,0,1] op_sel_hi:[0,1,0]
	v_pk_mul_f32 v[70:71], v[100:101], v[58:59]
	v_pk_mul_f32 v[66:67], v[100:101], v[58:59] op_sel:[1,0] op_sel_hi:[0,1]
	v_pk_fma_f32 v[58:59], v[100:101], v[54:55], v[66:67] neg_lo:[0,0,1] neg_hi:[0,0,1]
	v_pk_fma_f32 v[66:67], v[100:101], v[54:55], v[66:67]
	v_pk_fma_f32 v[68:69], v[100:101], v[54:55], v[70:71] op_sel:[0,1,1] op_sel_hi:[1,0,0] neg_lo:[0,0,1] neg_hi:[0,0,1]
	v_pk_fma_f32 v[54:55], v[100:101], v[54:55], v[70:71] op_sel:[0,1,1] op_sel_hi:[1,0,0]
	v_pk_mul_f32 v[74:75], v[100:101], v[48:49]
	v_pk_mul_f32 v[70:71], v[100:101], v[48:49] op_sel:[1,0] op_sel_hi:[0,1]
	v_pk_fma_f32 v[48:49], v[100:101], v[44:45], v[70:71] neg_lo:[0,0,1] neg_hi:[0,0,1]
	v_pk_fma_f32 v[70:71], v[100:101], v[44:45], v[70:71]
	v_pk_fma_f32 v[72:73], v[100:101], v[44:45], v[74:75] op_sel:[0,1,1] op_sel_hi:[1,0,0] neg_lo:[0,0,1] neg_hi:[0,0,1]
	v_pk_fma_f32 v[44:45], v[100:101], v[44:45], v[74:75] op_sel:[0,1,1] op_sel_hi:[1,0,0]
	v_pk_mul_f32 v[78:79], v[100:101], v[50:51]
	v_pk_mul_f32 v[74:75], v[100:101], v[50:51] op_sel:[1,0] op_sel_hi:[0,1]
	v_pk_fma_f32 v[50:51], v[100:101], v[46:47], v[74:75] neg_lo:[0,0,1] neg_hi:[0,0,1]
	v_pk_fma_f32 v[74:75], v[100:101], v[46:47], v[74:75]
	v_pk_fma_f32 v[76:77], v[100:101], v[46:47], v[78:79] op_sel:[0,1,1] op_sel_hi:[1,0,0] neg_lo:[0,0,1] neg_hi:[0,0,1]
	v_pk_fma_f32 v[46:47], v[100:101], v[46:47], v[78:79] op_sel:[0,1,1] op_sel_hi:[1,0,0]
	v_pk_mul_f32 v[82:83], v[100:101], v[40:41]
	v_pk_mul_f32 v[78:79], v[100:101], v[40:41] op_sel:[1,0] op_sel_hi:[0,1]
	v_pk_fma_f32 v[40:41], v[100:101], v[36:37], v[78:79] neg_lo:[0,0,1] neg_hi:[0,0,1]
	v_pk_fma_f32 v[78:79], v[100:101], v[36:37], v[78:79]
	v_pk_fma_f32 v[80:81], v[100:101], v[36:37], v[82:83] op_sel:[0,1,1] op_sel_hi:[1,0,0] neg_lo:[0,0,1] neg_hi:[0,0,1]
	v_pk_fma_f32 v[36:37], v[100:101], v[36:37], v[82:83] op_sel:[0,1,1] op_sel_hi:[1,0,0]
	v_pk_mul_f32 v[86:87], v[100:101], v[42:43]
	v_pk_mul_f32 v[82:83], v[100:101], v[42:43] op_sel:[1,0] op_sel_hi:[0,1]
	v_pk_mul_f32 v[92:93], v[100:101], v[32:33]
	v_pk_mul_f32 v[32:33], v[100:101], v[32:33] op_sel:[1,0] op_sel_hi:[0,1]
	v_pk_fma_f32 v[42:43], v[100:101], v[38:39], v[82:83] neg_lo:[0,0,1] neg_hi:[0,0,1]
	v_pk_fma_f32 v[82:83], v[100:101], v[38:39], v[82:83]
	v_pk_fma_f32 v[84:85], v[100:101], v[38:39], v[86:87] op_sel:[0,1,1] op_sel_hi:[1,0,0] neg_lo:[0,0,1] neg_hi:[0,0,1]
	v_pk_fma_f32 v[38:39], v[100:101], v[38:39], v[86:87] op_sel:[0,1,1] op_sel_hi:[1,0,0]
	v_pk_fma_f32 v[86:87], v[100:101], v[28:29], v[32:33] neg_lo:[0,0,1] neg_hi:[0,0,1]
	v_pk_fma_f32 v[88:89], v[100:101], v[28:29], v[32:33]
	v_pk_fma_f32 v[90:91], v[100:101], v[28:29], v[92:93] op_sel:[0,1,1] op_sel_hi:[1,0,0] neg_lo:[0,0,1] neg_hi:[0,0,1]
	v_pk_fma_f32 v[92:93], v[100:101], v[28:29], v[92:93] op_sel:[0,1,1] op_sel_hi:[1,0,0]
	v_pk_mul_f32 v[28:29], v[100:101], v[34:35]
	v_pk_mul_f32 v[32:33], v[100:101], v[34:35] op_sel:[1,0] op_sel_hi:[0,1]
	v_pk_fma_f32 v[94:95], v[100:101], v[30:31], v[32:33] neg_lo:[0,0,1] neg_hi:[0,0,1]
	v_pk_fma_f32 v[96:97], v[100:101], v[30:31], v[32:33]
	v_pk_fma_f32 v[98:99], v[100:101], v[30:31], v[28:29] op_sel:[0,1,1] op_sel_hi:[1,0,0] neg_lo:[0,0,1] neg_hi:[0,0,1]
	v_pk_fma_f32 v[100:101], v[100:101], v[30:31], v[28:29] op_sel:[0,1,1] op_sel_hi:[1,0,0]
	v_lshlrev_b32_e32 v28, 1, v105
	v_mov_b32_e32 v29, v0
	v_lshl_add_u64 v[28:29], s[24:25], 0, v[28:29]
	v_lshlrev_b64 v[30:31], 1, v[102:103]
	v_lshl_add_u64 v[102:103], s[24:25], 0, v[30:31]
	v_mul_u32_u24_e32 v3, 0x110, v105
	v_lshlrev_b32_e32 v40, 2, v104
	v_lshl_add_u64 v[104:105], v[28:29], 0, v[30:31]
	s_waitcnt vmcnt(1)
; __device__ __forceinline__ float bf2f(bf16_t v) { return __uint_as_float((unsigned)v << 16); }
; __device__ __forceinline__ float lo_f(unsigned w) { return __uint_as_float(w << 16); }
; __device__ __forceinline__ float hi_f(unsigned w) { return __uint_as_float(w & 0xffff0000u); }
; __device__ __forceinline__ float geluf_(float y) { const float a = 0.7978845608f * (y + 0.044715f * y * y * y); const float t = __expf(2.f * a); return 0.5f * y * (2.f - 2.f * __builtin_amdgcn_rcpf(t + 1.f)); }
; __device__ __forceinline__ bf16_t f2bf_(float v) { return (bf16_t)(pk2(v, v) & 0xffffu); }
; __device__ __forceinline__ void s5_item(CPar p, int l, int s, int g, float* wl) {
;     ...
;     for (int blk = 0; blk < nblk; ++blk) {
;         const int r0 = row_of(s, blk * 16);
;         const u32x4 ca = ua, cbv = ub;
;         if (blk + 1 < nblk && lane < 16) { const int r1 = row_of(s, blk * 16 + 16); const u32x4* up = (const u32x4*)(U + (size_t)(r1 + lane) * 512 + g * 16); ua = up[0]; ub = up[1]; }
; #pragma unroll
;         for (int i = 0; i < 16; ++i) {
;             float br4[4] = {0.f, 0.f, 0.f, 0.f}, bi4[4] = {0.f, 0.f, 0.f, 0.f};
; #pragma unroll
;             for (int w = 0; w < 8; ++w) { const unsigned word = (unsigned)__builtin_amdgcn_readlane((int)(w < 4 ? ca[w] : cbv[w - 4]), i);
;                 const float u0 = lo_f(word), u1 = hi_f(word);
;                 br4[w & 3] += bbr[2 * w] * u0 + bbr[2 * w + 1] * u1; bi4[w & 3] += bbi[2 * w] * u0 + bbi[2 * w + 1] * u1; }
;             const float bur = (br4[0] + br4[1]) + (br4[2] + br4[3]), bui = (bi4[0] + bi4[1]) + (bi4[2] + bi4[3]);
;             const float nxr = ab_re * xr - ab_im * xi + bur, nxi = ab_re * xi + ab_im * xr + bui; xr = nxr; xi = nxi;
;             Xb[i * LBX + lane] = f2bf_(xr); Xb[i * LBX + 64 + lane] = f2bf_(xi);
;     ...
;         for (int r = 0; r < 4; ++r) { bf16_t* up = U + (size_t)(r0 + fq * 4 + r) * 512 + g * 16 + fr; *up = f2bf_(geluf_(y[r] + dsk * bf2f(*up))); }
	v_mov_b64_e32 v[30:31], v[22:23]
	s_waitcnt vmcnt(0)
	v_mov_b64_e32 v[34:35], v[26:27]
	v_mov_b32_e32 v63, v57
	v_mov_b32_e32 v53, v65
	v_mov_b32_e32 v67, v59
	v_mov_b32_e32 v55, v69
	v_mov_b32_e32 v71, v49
	v_mov_b32_e32 v45, v73
	v_mov_b32_e32 v75, v51
	v_mov_b32_e32 v47, v77
	v_mov_b32_e32 v79, v41
	v_mov_b32_e32 v37, v81
	v_mov_b32_e32 v83, v43
	v_mov_b32_e32 v39, v85
	v_mov_b32_e32 v89, v87
	v_mov_b32_e32 v93, v91
	v_mov_b32_e32 v97, v95
	v_mov_b32_e32 v101, v99
	v_add3_u32 v1, s52, v3, v1
	v_lshl_add_u32 v42, v108, 1, s52
	v_mov_b32_e32 v3, v2
	v_mov_b32_e32 v61, v60
	v_mov_b64_e32 v[28:29], v[20:21]
	v_mov_b64_e32 v[32:33], v[24:25]
	v_mov_b32_e32 v216, v62
	v_mov_b32_e32 v217, v65
	v_mov_b32_e32 v218, v52
	v_mov_b32_e32 v219, v57
	v_mov_b32_e32 v220, v66
	v_mov_b32_e32 v221, v69
	v_mov_b32_e32 v222, v54
	v_mov_b32_e32 v223, v59
	v_mov_b32_e32 v224, v70
	v_mov_b32_e32 v225, v73
	v_mov_b32_e32 v226, v44
	v_mov_b32_e32 v227, v49
	v_mov_b32_e32 v228, v74
	v_mov_b32_e32 v229, v77
	v_mov_b32_e32 v230, v46
	v_mov_b32_e32 v231, v51
	v_mov_b32_e32 v232, v78
	v_mov_b32_e32 v233, v81
	v_mov_b32_e32 v234, v36
	v_mov_b32_e32 v235, v41
	v_mov_b32_e32 v236, v82
	v_mov_b32_e32 v237, v85
	v_mov_b32_e32 v238, v38
	v_mov_b32_e32 v239, v43
	v_mov_b32_e32 v240, v88
	v_mov_b32_e32 v241, v91
	v_mov_b32_e32 v242, v92
	v_mov_b32_e32 v243, v87
	v_mov_b32_e32 v244, v96
	v_mov_b32_e32 v245, v99
	v_mov_b32_e32 v246, v100
	v_mov_b32_e32 v247, v95
	s_branch .LBB0_681
.LBB0_680:
	s_or_b64 exec, exec, s[24:25]
	s_add_i32 s6, s11, -16
	s_cmp_eq_u32 s12, 0
	s_cselect_b32 s13, s10, s6
	v_or_b32_e32 v192, s13, v40
	v_ashrrev_i32_e32 v193, 31, v192
	v_lshlrev_b64 v[192:193], 10, v[192:193]
	v_lshl_add_u64 v[192:193], v[104:105], 0, v[192:193]
	global_load_ushort v194, v[192:193], off
	global_load_ushort v195, v[192:193], off offset:1024
	global_load_ushort v196, v[192:193], off offset:2048
	global_load_ushort v197, v[192:193], off offset:3072
	v_lshlrev_b32_e32 v176, 16, v24
	v_and_b32_e32 v177, 0xffff0000, v24
	v_lshlrev_b32_e32 v178, 16, v25
	v_and_b32_e32 v179, 0xffff0000, v25
	v_lshlrev_b32_e32 v180, 16, v26
	v_and_b32_e32 v181, 0xffff0000, v26
	v_lshlrev_b32_e32 v182, 16, v27
	v_and_b32_e32 v183, 0xffff0000, v27
	v_lshlrev_b32_e32 v184, 16, v20
	v_and_b32_e32 v185, 0xffff0000, v20
	v_lshlrev_b32_e32 v186, 16, v21
	v_and_b32_e32 v187, 0xffff0000, v21
	v_lshlrev_b32_e32 v188, 16, v22
	v_and_b32_e32 v189, 0xffff0000, v22
	v_lshlrev_b32_e32 v190, 16, v23
	v_and_b32_e32 v191, 0xffff0000, v23
	v_readlane_b32 s54, v176, 0
	v_readlane_b32 s55, v177, 0
	v_readlane_b32 s56, v178, 0
	v_readlane_b32 s57, v179, 0
	v_readlane_b32 s58, v180, 0
	v_readlane_b32 s59, v181, 0
	v_readlane_b32 s60, v182, 0
	v_readlane_b32 s61, v183, 0
	v_readlane_b32 s62, v184, 0
	v_readlane_b32 s63, v185, 0
	v_readlane_b32 s64, v186, 0
	v_readlane_b32 s65, v187, 0
	v_readlane_b32 s78, v188, 0
	v_readlane_b32 s79, v189, 0
	v_readlane_b32 s80, v190, 0
	v_readlane_b32 s81, v191, 0
	v_pk_mul_f32 v[248:249], v[216:217], s[54:55] op_sel_hi:[1,0]
	v_pk_mul_f32 v[250:251], v[218:219], s[54:55] op_sel:[0,1]
	v_pk_mul_f32 v[252:253], v[220:221], s[56:57] op_sel_hi:[1,0]
	v_pk_mul_f32 v[198:199], v[222:223], s[56:57] op_sel:[0,1]
	v_pk_fma_f32 v[248:249], v[224:225], s[58:59], v[248:249] op_sel_hi:[1,0,1]
	v_pk_fma_f32 v[250:251], v[226:227], s[58:59], v[250:251] op_sel:[0,1,0]
	v_pk_fma_f32 v[252:253], v[228:229], s[60:61], v[252:253] op_sel_hi:[1,0,1]
	v_pk_fma_f32 v[198:199], v[230:231], s[60:61], v[198:199] op_sel:[0,1,0]
	v_pk_fma_f32 v[248:249], v[232:233], s[62:63], v[248:249] op_sel_hi:[1,0,1]
	v_pk_fma_f32 v[250:251], v[234:235], s[62:63], v[250:251] op_sel:[0,1,0]
	v_pk_fma_f32 v[252:253], v[236:237], s[64:65], v[252:253] op_sel_hi:[1,0,1]
	v_pk_fma_f32 v[198:199], v[238:239], s[64:65], v[198:199] op_sel:[0,1,0]
	v_pk_fma_f32 v[248:249], v[240:241], s[78:79], v[248:249] op_sel_hi:[1,0,1]
	v_pk_fma_f32 v[250:251], v[242:243], s[78:79], v[250:251] op_sel:[0,1,0]
	v_pk_fma_f32 v[252:253], v[244:245], s[80:81], v[252:253] op_sel_hi:[1,0,1]
	v_pk_fma_f32 v[198:199], v[246:247], s[80:81], v[198:199] op_sel:[0,1,0]
	v_pk_add_f32 v[248:249], v[248:249], v[250:251]
	v_pk_add_f32 v[252:253], v[252:253], v[198:199]
	v_pk_add_f32 v[248:249], v[248:249], v[252:253]
	v_pk_fma_f32 v[248:249], v[106:107], v[2:3], v[248:249]
	v_pk_fma_f32 v[106:107], v[106:107], v[60:61], v[248:249] op_sel:[1,0,0] op_sel_hi:[0,1,1] neg_hi:[0,1,0]
	v_cvt_pk_bf16_f32 v140, v107, v107
	ds_write_b16 v42, v140
	v_cvt_pk_bf16_f32 v141, v106, v106
	ds_write_b16 v42, v141 offset:128
	v_readlane_b32 s54, v176, 1
	v_readlane_b32 s55, v177, 1
	v_readlane_b32 s56, v178, 1
	v_readlane_b32 s57, v179, 1
	v_readlane_b32 s58, v180, 1
	v_readlane_b32 s59, v181, 1
	v_readlane_b32 s60, v182, 1
	v_readlane_b32 s61, v183, 1
	v_readlane_b32 s62, v184, 1
	v_readlane_b32 s63, v185, 1
	v_readlane_b32 s64, v186, 1
	v_readlane_b32 s65, v187, 1
	v_readlane_b32 s78, v188, 1
	v_readlane_b32 s79, v189, 1
	v_readlane_b32 s80, v190, 1
	v_readlane_b32 s81, v191, 1
	v_pk_mul_f32 v[248:249], v[216:217], s[54:55] op_sel_hi:[1,0]
	v_pk_mul_f32 v[250:251], v[218:219], s[54:55] op_sel:[0,1]
	v_pk_mul_f32 v[252:253], v[220:221], s[56:57] op_sel_hi:[1,0]
	v_pk_mul_f32 v[198:199], v[222:223], s[56:57] op_sel:[0,1]
	v_pk_fma_f32 v[248:249], v[224:225], s[58:59], v[248:249] op_sel_hi:[1,0,1]
	v_pk_fma_f32 v[250:251], v[226:227], s[58:59], v[250:251] op_sel:[0,1,0]
	v_pk_fma_f32 v[252:253], v[228:229], s[60:61], v[252:253] op_sel_hi:[1,0,1]
	v_pk_fma_f32 v[198:199], v[230:231], s[60:61], v[198:199] op_sel:[0,1,0]
	v_pk_fma_f32 v[248:249], v[232:233], s[62:63], v[248:249] op_sel_hi:[1,0,1]
; __device__ __forceinline__ float lo_f(unsigned w) { return __uint_as_float(w << 16); }
; __device__ __forceinline__ float hi_f(unsigned w) { return __uint_as_float(w & 0xffff0000u); }
; __device__ __forceinline__ bf16_t f2bf_(float v) { return (bf16_t)(pk2(v, v) & 0xffffu); }
; __device__ __forceinline__ void s5_item(CPar p, int l, int s, int g, float* wl) {
;     ...
;         for (int i = 0; i < 16; ++i) {
;             float br4[4] = {0.f, 0.f, 0.f, 0.f}, bi4[4] = {0.f, 0.f, 0.f, 0.f};
; #pragma unroll
;             for (int w = 0; w < 8; ++w) { const unsigned word = (unsigned)__builtin_amdgcn_readlane((int)(w < 4 ? ca[w] : cbv[w - 4]), i);
;                 const float u0 = lo_f(word), u1 = hi_f(word);
;                 br4[w & 3] += bbr[2 * w] * u0 + bbr[2 * w + 1] * u1; bi4[w & 3] += bbi[2 * w] * u0 + bbi[2 * w + 1] * u1; }
;             const float bur = (br4[0] + br4[1]) + (br4[2] + br4[3]), bui = (bi4[0] + bi4[1]) + (bi4[2] + bi4[3]);
;             const float nxr = ab_re * xr - ab_im * xi + bur, nxi = ab_re * xi + ab_im * xr + bui; xr = nxr; xi = nxi;
;             Xb[i * LBX + lane] = f2bf_(xr); Xb[i * LBX + 64 + lane] = f2bf_(xi);
	v_pk_fma_f32 v[250:251], v[234:235], s[62:63], v[250:251] op_sel:[0,1,0]
	v_pk_fma_f32 v[252:253], v[236:237], s[64:65], v[252:253] op_sel_hi:[1,0,1]
	v_pk_fma_f32 v[198:199], v[238:239], s[64:65], v[198:199] op_sel:[0,1,0]
	v_pk_fma_f32 v[248:249], v[240:241], s[78:79], v[248:249] op_sel_hi:[1,0,1]
	v_pk_fma_f32 v[250:251], v[242:243], s[78:79], v[250:251] op_sel:[0,1,0]
	v_pk_fma_f32 v[252:253], v[244:245], s[80:81], v[252:253] op_sel_hi:[1,0,1]
	v_pk_fma_f32 v[198:199], v[246:247], s[80:81], v[198:199] op_sel:[0,1,0]
	v_pk_add_f32 v[248:249], v[248:249], v[250:251]
	v_pk_add_f32 v[252:253], v[252:253], v[198:199]
	v_pk_add_f32 v[248:249], v[248:249], v[252:253]
	v_pk_fma_f32 v[248:249], v[106:107], v[2:3], v[248:249]
	v_pk_fma_f32 v[106:107], v[106:107], v[60:61], v[248:249] op_sel:[1,0,0] op_sel_hi:[0,1,1] neg_hi:[0,1,0]
	v_cvt_pk_bf16_f32 v140, v107, v107
	ds_write_b16 v42, v140 offset:272
	v_cvt_pk_bf16_f32 v141, v106, v106
	ds_write_b16 v42, v141 offset:400
	v_readlane_b32 s54, v176, 2
	v_readlane_b32 s55, v177, 2
	v_readlane_b32 s56, v178, 2
	v_readlane_b32 s57, v179, 2
	v_readlane_b32 s58, v180, 2
	v_readlane_b32 s59, v181, 2
	v_readlane_b32 s60, v182, 2
	v_readlane_b32 s61, v183, 2
	v_readlane_b32 s62, v184, 2
	v_readlane_b32 s63, v185, 2
	v_readlane_b32 s64, v186, 2
	v_readlane_b32 s65, v187, 2
	v_readlane_b32 s78, v188, 2
	v_readlane_b32 s79, v189, 2
	v_readlane_b32 s80, v190, 2
	v_readlane_b32 s81, v191, 2
	v_pk_mul_f32 v[248:249], v[216:217], s[54:55] op_sel_hi:[1,0]
	v_pk_mul_f32 v[250:251], v[218:219], s[54:55] op_sel:[0,1]
	v_pk_mul_f32 v[252:253], v[220:221], s[56:57] op_sel_hi:[1,0]
	v_pk_mul_f32 v[198:199], v[222:223], s[56:57] op_sel:[0,1]
	v_pk_fma_f32 v[248:249], v[224:225], s[58:59], v[248:249] op_sel_hi:[1,0,1]
	v_pk_fma_f32 v[250:251], v[226:227], s[58:59], v[250:251] op_sel:[0,1,0]
	v_pk_fma_f32 v[252:253], v[228:229], s[60:61], v[252:253] op_sel_hi:[1,0,1]
	v_pk_fma_f32 v[198:199], v[230:231], s[60:61], v[198:199] op_sel:[0,1,0]
	v_pk_fma_f32 v[248:249], v[232:233], s[62:63], v[248:249] op_sel_hi:[1,0,1]
	v_pk_fma_f32 v[250:251], v[234:235], s[62:63], v[250:251] op_sel:[0,1,0]
	v_pk_fma_f32 v[252:253], v[236:237], s[64:65], v[252:253] op_sel_hi:[1,0,1]
	v_pk_fma_f32 v[198:199], v[238:239], s[64:65], v[198:199] op_sel:[0,1,0]
	v_pk_fma_f32 v[248:249], v[240:241], s[78:79], v[248:249] op_sel_hi:[1,0,1]
	v_pk_fma_f32 v[250:251], v[242:243], s[78:79], v[250:251] op_sel:[0,1,0]
	v_pk_fma_f32 v[252:253], v[244:245], s[80:81], v[252:253] op_sel_hi:[1,0,1]
	v_pk_fma_f32 v[198:199], v[246:247], s[80:81], v[198:199] op_sel:[0,1,0]
	v_pk_add_f32 v[248:249], v[248:249], v[250:251]
	v_pk_add_f32 v[252:253], v[252:253], v[198:199]
	v_pk_add_f32 v[248:249], v[248:249], v[252:253]
	v_pk_fma_f32 v[248:249], v[106:107], v[2:3], v[248:249]
	v_pk_fma_f32 v[106:107], v[106:107], v[60:61], v[248:249] op_sel:[1,0,0] op_sel_hi:[0,1,1] neg_hi:[0,1,0]
	v_cvt_pk_bf16_f32 v140, v107, v107
	ds_write_b16 v42, v140 offset:544
	v_cvt_pk_bf16_f32 v141, v106, v106
	ds_write_b16 v42, v141 offset:672
	v_readlane_b32 s54, v176, 3
	v_readlane_b32 s55, v177, 3
	v_readlane_b32 s56, v178, 3
	v_readlane_b32 s57, v179, 3
	v_readlane_b32 s58, v180, 3
	v_readlane_b32 s59, v181, 3
	v_readlane_b32 s60, v182, 3
	v_readlane_b32 s61, v183, 3
	v_readlane_b32 s62, v184, 3
	v_readlane_b32 s63, v185, 3
	v_readlane_b32 s64, v186, 3
	v_readlane_b32 s65, v187, 3
	v_readlane_b32 s78, v188, 3
	v_readlane_b32 s79, v189, 3
	v_readlane_b32 s80, v190, 3
	v_readlane_b32 s81, v191, 3
	v_pk_mul_f32 v[248:249], v[216:217], s[54:55] op_sel_hi:[1,0]
	v_pk_mul_f32 v[250:251], v[218:219], s[54:55] op_sel:[0,1]
	v_pk_mul_f32 v[252:253], v[220:221], s[56:57] op_sel_hi:[1,0]
	v_pk_mul_f32 v[198:199], v[222:223], s[56:57] op_sel:[0,1]
	v_pk_fma_f32 v[248:249], v[224:225], s[58:59], v[248:249] op_sel_hi:[1,0,1]
	v_pk_fma_f32 v[250:251], v[226:227], s[58:59], v[250:251] op_sel:[0,1,0]
	v_pk_fma_f32 v[252:253], v[228:229], s[60:61], v[252:253] op_sel_hi:[1,0,1]
	v_pk_fma_f32 v[198:199], v[230:231], s[60:61], v[198:199] op_sel:[0,1,0]
	v_pk_fma_f32 v[248:249], v[232:233], s[62:63], v[248:249] op_sel_hi:[1,0,1]
	v_pk_fma_f32 v[250:251], v[234:235], s[62:63], v[250:251] op_sel:[0,1,0]
	v_pk_fma_f32 v[252:253], v[236:237], s[64:65], v[252:253] op_sel_hi:[1,0,1]
	v_pk_fma_f32 v[198:199], v[238:239], s[64:65], v[198:199] op_sel:[0,1,0]
	v_pk_fma_f32 v[248:249], v[240:241], s[78:79], v[248:249] op_sel_hi:[1,0,1]
	v_pk_fma_f32 v[250:251], v[242:243], s[78:79], v[250:251] op_sel:[0,1,0]
	v_pk_fma_f32 v[252:253], v[244:245], s[80:81], v[252:253] op_sel_hi:[1,0,1]
	v_pk_fma_f32 v[198:199], v[246:247], s[80:81], v[198:199] op_sel:[0,1,0]
	v_pk_add_f32 v[248:249], v[248:249], v[250:251]
	v_pk_add_f32 v[252:253], v[252:253], v[198:199]
	v_pk_add_f32 v[248:249], v[248:249], v[252:253]
	v_pk_fma_f32 v[248:249], v[106:107], v[2:3], v[248:249]
	v_pk_fma_f32 v[106:107], v[106:107], v[60:61], v[248:249] op_sel:[1,0,0] op_sel_hi:[0,1,1] neg_hi:[0,1,0]
	v_cvt_pk_bf16_f32 v140, v107, v107
	ds_write_b16 v42, v140 offset:816
	v_cvt_pk_bf16_f32 v141, v106, v106
	ds_write_b16 v42, v141 offset:944
	v_readlane_b32 s54, v176, 4
	v_readlane_b32 s55, v177, 4
	v_readlane_b32 s56, v178, 4
	v_readlane_b32 s57, v179, 4
	v_readlane_b32 s58, v180, 4
	v_readlane_b32 s59, v181, 4
	v_readlane_b32 s60, v182, 4
	v_readlane_b32 s61, v183, 4
	v_readlane_b32 s62, v184, 4
	v_readlane_b32 s63, v185, 4
	v_readlane_b32 s64, v186, 4
	v_readlane_b32 s65, v187, 4
	v_readlane_b32 s78, v188, 4
	v_readlane_b32 s79, v189, 4
	v_readlane_b32 s80, v190, 4
	v_readlane_b32 s81, v191, 4
	v_pk_mul_f32 v[248:249], v[216:217], s[54:55] op_sel_hi:[1,0]
; __device__ __forceinline__ float lo_f(unsigned w) { return __uint_as_float(w << 16); }
; __device__ __forceinline__ float hi_f(unsigned w) { return __uint_as_float(w & 0xffff0000u); }
; __device__ __forceinline__ bf16_t f2bf_(float v) { return (bf16_t)(pk2(v, v) & 0xffffu); }
; __device__ __forceinline__ void s5_item(CPar p, int l, int s, int g, float* wl) {
;     ...
;         for (int i = 0; i < 16; ++i) {
;             float br4[4] = {0.f, 0.f, 0.f, 0.f}, bi4[4] = {0.f, 0.f, 0.f, 0.f};
; #pragma unroll
;             for (int w = 0; w < 8; ++w) { const unsigned word = (unsigned)__builtin_amdgcn_readlane((int)(w < 4 ? ca[w] : cbv[w - 4]), i);
;                 const float u0 = lo_f(word), u1 = hi_f(word);
;                 br4[w & 3] += bbr[2 * w] * u0 + bbr[2 * w + 1] * u1; bi4[w & 3] += bbi[2 * w] * u0 + bbi[2 * w + 1] * u1; }
;             const float bur = (br4[0] + br4[1]) + (br4[2] + br4[3]), bui = (bi4[0] + bi4[1]) + (bi4[2] + bi4[3]);
;             const float nxr = ab_re * xr - ab_im * xi + bur, nxi = ab_re * xi + ab_im * xr + bui; xr = nxr; xi = nxi;
;             Xb[i * LBX + lane] = f2bf_(xr); Xb[i * LBX + 64 + lane] = f2bf_(xi);
	v_pk_mul_f32 v[250:251], v[218:219], s[54:55] op_sel:[0,1]
	v_pk_mul_f32 v[252:253], v[220:221], s[56:57] op_sel_hi:[1,0]
	v_pk_mul_f32 v[198:199], v[222:223], s[56:57] op_sel:[0,1]
	v_pk_fma_f32 v[248:249], v[224:225], s[58:59], v[248:249] op_sel_hi:[1,0,1]
	v_pk_fma_f32 v[250:251], v[226:227], s[58:59], v[250:251] op_sel:[0,1,0]
	v_pk_fma_f32 v[252:253], v[228:229], s[60:61], v[252:253] op_sel_hi:[1,0,1]
	v_pk_fma_f32 v[198:199], v[230:231], s[60:61], v[198:199] op_sel:[0,1,0]
	v_pk_fma_f32 v[248:249], v[232:233], s[62:63], v[248:249] op_sel_hi:[1,0,1]
	v_pk_fma_f32 v[250:251], v[234:235], s[62:63], v[250:251] op_sel:[0,1,0]
	v_pk_fma_f32 v[252:253], v[236:237], s[64:65], v[252:253] op_sel_hi:[1,0,1]
	v_pk_fma_f32 v[198:199], v[238:239], s[64:65], v[198:199] op_sel:[0,1,0]
	v_pk_fma_f32 v[248:249], v[240:241], s[78:79], v[248:249] op_sel_hi:[1,0,1]
	v_pk_fma_f32 v[250:251], v[242:243], s[78:79], v[250:251] op_sel:[0,1,0]
	v_pk_fma_f32 v[252:253], v[244:245], s[80:81], v[252:253] op_sel_hi:[1,0,1]
	v_pk_fma_f32 v[198:199], v[246:247], s[80:81], v[198:199] op_sel:[0,1,0]
	v_pk_add_f32 v[248:249], v[248:249], v[250:251]
	v_pk_add_f32 v[252:253], v[252:253], v[198:199]
	v_pk_add_f32 v[248:249], v[248:249], v[252:253]
	v_pk_fma_f32 v[248:249], v[106:107], v[2:3], v[248:249]
	v_pk_fma_f32 v[106:107], v[106:107], v[60:61], v[248:249] op_sel:[1,0,0] op_sel_hi:[0,1,1] neg_hi:[0,1,0]
	v_cvt_pk_bf16_f32 v140, v107, v107
	ds_write_b16 v42, v140 offset:1088
	v_cvt_pk_bf16_f32 v141, v106, v106
	ds_write_b16 v42, v141 offset:1216
	v_readlane_b32 s54, v176, 5
	v_readlane_b32 s55, v177, 5
	v_readlane_b32 s56, v178, 5
	v_readlane_b32 s57, v179, 5
	v_readlane_b32 s58, v180, 5
	v_readlane_b32 s59, v181, 5
	v_readlane_b32 s60, v182, 5
	v_readlane_b32 s61, v183, 5
	v_readlane_b32 s62, v184, 5
	v_readlane_b32 s63, v185, 5
	v_readlane_b32 s64, v186, 5
	v_readlane_b32 s65, v187, 5
	v_readlane_b32 s78, v188, 5
	v_readlane_b32 s79, v189, 5
	v_readlane_b32 s80, v190, 5
	v_readlane_b32 s81, v191, 5
	v_pk_mul_f32 v[248:249], v[216:217], s[54:55] op_sel_hi:[1,0]
	v_pk_mul_f32 v[250:251], v[218:219], s[54:55] op_sel:[0,1]
	v_pk_mul_f32 v[252:253], v[220:221], s[56:57] op_sel_hi:[1,0]
	v_pk_mul_f32 v[198:199], v[222:223], s[56:57] op_sel:[0,1]
	v_pk_fma_f32 v[248:249], v[224:225], s[58:59], v[248:249] op_sel_hi:[1,0,1]
	v_pk_fma_f32 v[250:251], v[226:227], s[58:59], v[250:251] op_sel:[0,1,0]
	v_pk_fma_f32 v[252:253], v[228:229], s[60:61], v[252:253] op_sel_hi:[1,0,1]
	v_pk_fma_f32 v[198:199], v[230:231], s[60:61], v[198:199] op_sel:[0,1,0]
	v_pk_fma_f32 v[248:249], v[232:233], s[62:63], v[248:249] op_sel_hi:[1,0,1]
	v_pk_fma_f32 v[250:251], v[234:235], s[62:63], v[250:251] op_sel:[0,1,0]
	v_pk_fma_f32 v[252:253], v[236:237], s[64:65], v[252:253] op_sel_hi:[1,0,1]
	v_pk_fma_f32 v[198:199], v[238:239], s[64:65], v[198:199] op_sel:[0,1,0]
	v_pk_fma_f32 v[248:249], v[240:241], s[78:79], v[248:249] op_sel_hi:[1,0,1]
	v_pk_fma_f32 v[250:251], v[242:243], s[78:79], v[250:251] op_sel:[0,1,0]
	v_pk_fma_f32 v[252:253], v[244:245], s[80:81], v[252:253] op_sel_hi:[1,0,1]
	v_pk_fma_f32 v[198:199], v[246:247], s[80:81], v[198:199] op_sel:[0,1,0]
	v_pk_add_f32 v[248:249], v[248:249], v[250:251]
	v_pk_add_f32 v[252:253], v[252:253], v[198:199]
	v_pk_add_f32 v[248:249], v[248:249], v[252:253]
	v_pk_fma_f32 v[248:249], v[106:107], v[2:3], v[248:249]
	v_pk_fma_f32 v[106:107], v[106:107], v[60:61], v[248:249] op_sel:[1,0,0] op_sel_hi:[0,1,1] neg_hi:[0,1,0]
	v_cvt_pk_bf16_f32 v140, v107, v107
	ds_write_b16 v42, v140 offset:1360
	v_cvt_pk_bf16_f32 v141, v106, v106
	ds_write_b16 v42, v141 offset:1488
	v_readlane_b32 s54, v176, 6
	v_readlane_b32 s55, v177, 6
	v_readlane_b32 s56, v178, 6
	v_readlane_b32 s57, v179, 6
	v_readlane_b32 s58, v180, 6
	v_readlane_b32 s59, v181, 6
	v_readlane_b32 s60, v182, 6
	v_readlane_b32 s61, v183, 6
	v_readlane_b32 s62, v184, 6
	v_readlane_b32 s63, v185, 6
	v_readlane_b32 s64, v186, 6
	v_readlane_b32 s65, v187, 6
	v_readlane_b32 s78, v188, 6
	v_readlane_b32 s79, v189, 6
	v_readlane_b32 s80, v190, 6
	v_readlane_b32 s81, v191, 6
	v_pk_mul_f32 v[248:249], v[216:217], s[54:55] op_sel_hi:[1,0]
	v_pk_mul_f32 v[250:251], v[218:219], s[54:55] op_sel:[0,1]
	v_pk_mul_f32 v[252:253], v[220:221], s[56:57] op_sel_hi:[1,0]
	v_pk_mul_f32 v[198:199], v[222:223], s[56:57] op_sel:[0,1]
	v_pk_fma_f32 v[248:249], v[224:225], s[58:59], v[248:249] op_sel_hi:[1,0,1]
	v_pk_fma_f32 v[250:251], v[226:227], s[58:59], v[250:251] op_sel:[0,1,0]
	v_pk_fma_f32 v[252:253], v[228:229], s[60:61], v[252:253] op_sel_hi:[1,0,1]
	v_pk_fma_f32 v[198:199], v[230:231], s[60:61], v[198:199] op_sel:[0,1,0]
	v_pk_fma_f32 v[248:249], v[232:233], s[62:63], v[248:249] op_sel_hi:[1,0,1]
	v_pk_fma_f32 v[250:251], v[234:235], s[62:63], v[250:251] op_sel:[0,1,0]
	v_pk_fma_f32 v[252:253], v[236:237], s[64:65], v[252:253] op_sel_hi:[1,0,1]
	v_pk_fma_f32 v[198:199], v[238:239], s[64:65], v[198:199] op_sel:[0,1,0]
	v_pk_fma_f32 v[248:249], v[240:241], s[78:79], v[248:249] op_sel_hi:[1,0,1]
	v_pk_fma_f32 v[250:251], v[242:243], s[78:79], v[250:251] op_sel:[0,1,0]
	v_pk_fma_f32 v[252:253], v[244:245], s[80:81], v[252:253] op_sel_hi:[1,0,1]
	v_pk_fma_f32 v[198:199], v[246:247], s[80:81], v[198:199] op_sel:[0,1,0]
	v_pk_add_f32 v[248:249], v[248:249], v[250:251]
	v_pk_add_f32 v[252:253], v[252:253], v[198:199]
	v_pk_add_f32 v[248:249], v[248:249], v[252:253]
	v_pk_fma_f32 v[248:249], v[106:107], v[2:3], v[248:249]
	v_pk_fma_f32 v[106:107], v[106:107], v[60:61], v[248:249] op_sel:[1,0,0] op_sel_hi:[0,1,1] neg_hi:[0,1,0]
	v_cvt_pk_bf16_f32 v140, v107, v107
	ds_write_b16 v42, v140 offset:1632
	v_cvt_pk_bf16_f32 v141, v106, v106
; __device__ __forceinline__ float lo_f(unsigned w) { return __uint_as_float(w << 16); }
; __device__ __forceinline__ float hi_f(unsigned w) { return __uint_as_float(w & 0xffff0000u); }
; __device__ __forceinline__ bf16_t f2bf_(float v) { return (bf16_t)(pk2(v, v) & 0xffffu); }
; __device__ __forceinline__ void s5_item(CPar p, int l, int s, int g, float* wl) {
;     ...
;         for (int i = 0; i < 16; ++i) {
;             float br4[4] = {0.f, 0.f, 0.f, 0.f}, bi4[4] = {0.f, 0.f, 0.f, 0.f};
; #pragma unroll
;             for (int w = 0; w < 8; ++w) { const unsigned word = (unsigned)__builtin_amdgcn_readlane((int)(w < 4 ? ca[w] : cbv[w - 4]), i);
;                 const float u0 = lo_f(word), u1 = hi_f(word);
;                 br4[w & 3] += bbr[2 * w] * u0 + bbr[2 * w + 1] * u1; bi4[w & 3] += bbi[2 * w] * u0 + bbi[2 * w + 1] * u1; }
;             const float bur = (br4[0] + br4[1]) + (br4[2] + br4[3]), bui = (bi4[0] + bi4[1]) + (bi4[2] + bi4[3]);
;             const float nxr = ab_re * xr - ab_im * xi + bur, nxi = ab_re * xi + ab_im * xr + bui; xr = nxr; xi = nxi;
;             Xb[i * LBX + lane] = f2bf_(xr); Xb[i * LBX + 64 + lane] = f2bf_(xi);
	ds_write_b16 v42, v141 offset:1760
	v_readlane_b32 s54, v176, 7
	v_readlane_b32 s55, v177, 7
	v_readlane_b32 s56, v178, 7
	v_readlane_b32 s57, v179, 7
	v_readlane_b32 s58, v180, 7
	v_readlane_b32 s59, v181, 7
	v_readlane_b32 s60, v182, 7
	v_readlane_b32 s61, v183, 7
	v_readlane_b32 s62, v184, 7
	v_readlane_b32 s63, v185, 7
	v_readlane_b32 s64, v186, 7
	v_readlane_b32 s65, v187, 7
	v_readlane_b32 s78, v188, 7
	v_readlane_b32 s79, v189, 7
	v_readlane_b32 s80, v190, 7
	v_readlane_b32 s81, v191, 7
	v_pk_mul_f32 v[248:249], v[216:217], s[54:55] op_sel_hi:[1,0]
	v_pk_mul_f32 v[250:251], v[218:219], s[54:55] op_sel:[0,1]
	v_pk_mul_f32 v[252:253], v[220:221], s[56:57] op_sel_hi:[1,0]
	v_pk_mul_f32 v[198:199], v[222:223], s[56:57] op_sel:[0,1]
	v_pk_fma_f32 v[248:249], v[224:225], s[58:59], v[248:249] op_sel_hi:[1,0,1]
	v_pk_fma_f32 v[250:251], v[226:227], s[58:59], v[250:251] op_sel:[0,1,0]
	v_pk_fma_f32 v[252:253], v[228:229], s[60:61], v[252:253] op_sel_hi:[1,0,1]
	v_pk_fma_f32 v[198:199], v[230:231], s[60:61], v[198:199] op_sel:[0,1,0]
	v_pk_fma_f32 v[248:249], v[232:233], s[62:63], v[248:249] op_sel_hi:[1,0,1]
	v_pk_fma_f32 v[250:251], v[234:235], s[62:63], v[250:251] op_sel:[0,1,0]
	v_pk_fma_f32 v[252:253], v[236:237], s[64:65], v[252:253] op_sel_hi:[1,0,1]
	v_pk_fma_f32 v[198:199], v[238:239], s[64:65], v[198:199] op_sel:[0,1,0]
	v_pk_fma_f32 v[248:249], v[240:241], s[78:79], v[248:249] op_sel_hi:[1,0,1]
	v_pk_fma_f32 v[250:251], v[242:243], s[78:79], v[250:251] op_sel:[0,1,0]
	v_pk_fma_f32 v[252:253], v[244:245], s[80:81], v[252:253] op_sel_hi:[1,0,1]
	v_pk_fma_f32 v[198:199], v[246:247], s[80:81], v[198:199] op_sel:[0,1,0]
	v_pk_add_f32 v[248:249], v[248:249], v[250:251]
	v_pk_add_f32 v[252:253], v[252:253], v[198:199]
	v_pk_add_f32 v[248:249], v[248:249], v[252:253]
	v_pk_fma_f32 v[248:249], v[106:107], v[2:3], v[248:249]
	v_pk_fma_f32 v[106:107], v[106:107], v[60:61], v[248:249] op_sel:[1,0,0] op_sel_hi:[0,1,1] neg_hi:[0,1,0]
	v_cvt_pk_bf16_f32 v140, v107, v107
	ds_write_b16 v42, v140 offset:1904
	v_cvt_pk_bf16_f32 v141, v106, v106
	ds_write_b16 v42, v141 offset:2032
	v_readlane_b32 s54, v176, 8
	v_readlane_b32 s55, v177, 8
	v_readlane_b32 s56, v178, 8
	v_readlane_b32 s57, v179, 8
	v_readlane_b32 s58, v180, 8
	v_readlane_b32 s59, v181, 8
	v_readlane_b32 s60, v182, 8
	v_readlane_b32 s61, v183, 8
	v_readlane_b32 s62, v184, 8
	v_readlane_b32 s63, v185, 8
	v_readlane_b32 s64, v186, 8
	v_readlane_b32 s65, v187, 8
	v_readlane_b32 s78, v188, 8
	v_readlane_b32 s79, v189, 8
	v_readlane_b32 s80, v190, 8
	v_readlane_b32 s81, v191, 8
	v_pk_mul_f32 v[248:249], v[216:217], s[54:55] op_sel_hi:[1,0]
	v_pk_mul_f32 v[250:251], v[218:219], s[54:55] op_sel:[0,1]
	v_pk_mul_f32 v[252:253], v[220:221], s[56:57] op_sel_hi:[1,0]
	v_pk_mul_f32 v[198:199], v[222:223], s[56:57] op_sel:[0,1]
	v_pk_fma_f32 v[248:249], v[224:225], s[58:59], v[248:249] op_sel_hi:[1,0,1]
	v_pk_fma_f32 v[250:251], v[226:227], s[58:59], v[250:251] op_sel:[0,1,0]
	v_pk_fma_f32 v[252:253], v[228:229], s[60:61], v[252:253] op_sel_hi:[1,0,1]
	v_pk_fma_f32 v[198:199], v[230:231], s[60:61], v[198:199] op_sel:[0,1,0]
	v_pk_fma_f32 v[248:249], v[232:233], s[62:63], v[248:249] op_sel_hi:[1,0,1]
	v_pk_fma_f32 v[250:251], v[234:235], s[62:63], v[250:251] op_sel:[0,1,0]
	v_pk_fma_f32 v[252:253], v[236:237], s[64:65], v[252:253] op_sel_hi:[1,0,1]
	v_pk_fma_f32 v[198:199], v[238:239], s[64:65], v[198:199] op_sel:[0,1,0]
	v_pk_fma_f32 v[248:249], v[240:241], s[78:79], v[248:249] op_sel_hi:[1,0,1]
	v_pk_fma_f32 v[250:251], v[242:243], s[78:79], v[250:251] op_sel:[0,1,0]
	v_pk_fma_f32 v[252:253], v[244:245], s[80:81], v[252:253] op_sel_hi:[1,0,1]
	v_pk_fma_f32 v[198:199], v[246:247], s[80:81], v[198:199] op_sel:[0,1,0]
	v_pk_add_f32 v[248:249], v[248:249], v[250:251]
	v_pk_add_f32 v[252:253], v[252:253], v[198:199]
	v_pk_add_f32 v[248:249], v[248:249], v[252:253]
	v_pk_fma_f32 v[248:249], v[106:107], v[2:3], v[248:249]
	v_pk_fma_f32 v[106:107], v[106:107], v[60:61], v[248:249] op_sel:[1,0,0] op_sel_hi:[0,1,1] neg_hi:[0,1,0]
	v_cvt_pk_bf16_f32 v140, v107, v107
	ds_write_b16 v42, v140 offset:2176
	v_cvt_pk_bf16_f32 v141, v106, v106
	ds_write_b16 v42, v141 offset:2304
	v_readlane_b32 s54, v176, 9
	v_readlane_b32 s55, v177, 9
	v_readlane_b32 s56, v178, 9
	v_readlane_b32 s57, v179, 9
	v_readlane_b32 s58, v180, 9
	v_readlane_b32 s59, v181, 9
	v_readlane_b32 s60, v182, 9
	v_readlane_b32 s61, v183, 9
	v_readlane_b32 s62, v184, 9
	v_readlane_b32 s63, v185, 9
	v_readlane_b32 s64, v186, 9
	v_readlane_b32 s65, v187, 9
	v_readlane_b32 s78, v188, 9
	v_readlane_b32 s79, v189, 9
	v_readlane_b32 s80, v190, 9
	v_readlane_b32 s81, v191, 9
	v_pk_mul_f32 v[248:249], v[216:217], s[54:55] op_sel_hi:[1,0]
	v_pk_mul_f32 v[250:251], v[218:219], s[54:55] op_sel:[0,1]
	v_pk_mul_f32 v[252:253], v[220:221], s[56:57] op_sel_hi:[1,0]
	v_pk_mul_f32 v[198:199], v[222:223], s[56:57] op_sel:[0,1]
	v_pk_fma_f32 v[248:249], v[224:225], s[58:59], v[248:249] op_sel_hi:[1,0,1]
	v_pk_fma_f32 v[250:251], v[226:227], s[58:59], v[250:251] op_sel:[0,1,0]
	v_pk_fma_f32 v[252:253], v[228:229], s[60:61], v[252:253] op_sel_hi:[1,0,1]
	v_pk_fma_f32 v[198:199], v[230:231], s[60:61], v[198:199] op_sel:[0,1,0]
	v_pk_fma_f32 v[248:249], v[232:233], s[62:63], v[248:249] op_sel_hi:[1,0,1]
	v_pk_fma_f32 v[250:251], v[234:235], s[62:63], v[250:251] op_sel:[0,1,0]
	v_pk_fma_f32 v[252:253], v[236:237], s[64:65], v[252:253] op_sel_hi:[1,0,1]
	v_pk_fma_f32 v[198:199], v[238:239], s[64:65], v[198:199] op_sel:[0,1,0]
	v_pk_fma_f32 v[248:249], v[240:241], s[78:79], v[248:249] op_sel_hi:[1,0,1]
	v_pk_fma_f32 v[250:251], v[242:243], s[78:79], v[250:251] op_sel:[0,1,0]
; __device__ __forceinline__ float lo_f(unsigned w) { return __uint_as_float(w << 16); }
; __device__ __forceinline__ float hi_f(unsigned w) { return __uint_as_float(w & 0xffff0000u); }
; __device__ __forceinline__ bf16_t f2bf_(float v) { return (bf16_t)(pk2(v, v) & 0xffffu); }
; __device__ __forceinline__ void s5_item(CPar p, int l, int s, int g, float* wl) {
;     ...
;         for (int i = 0; i < 16; ++i) {
;             float br4[4] = {0.f, 0.f, 0.f, 0.f}, bi4[4] = {0.f, 0.f, 0.f, 0.f};
; #pragma unroll
;             for (int w = 0; w < 8; ++w) { const unsigned word = (unsigned)__builtin_amdgcn_readlane((int)(w < 4 ? ca[w] : cbv[w - 4]), i);
;                 const float u0 = lo_f(word), u1 = hi_f(word);
;                 br4[w & 3] += bbr[2 * w] * u0 + bbr[2 * w + 1] * u1; bi4[w & 3] += bbi[2 * w] * u0 + bbi[2 * w + 1] * u1; }
;             const float bur = (br4[0] + br4[1]) + (br4[2] + br4[3]), bui = (bi4[0] + bi4[1]) + (bi4[2] + bi4[3]);
;             const float nxr = ab_re * xr - ab_im * xi + bur, nxi = ab_re * xi + ab_im * xr + bui; xr = nxr; xi = nxi;
;             Xb[i * LBX + lane] = f2bf_(xr); Xb[i * LBX + 64 + lane] = f2bf_(xi);
	v_pk_fma_f32 v[252:253], v[244:245], s[80:81], v[252:253] op_sel_hi:[1,0,1]
	v_pk_fma_f32 v[198:199], v[246:247], s[80:81], v[198:199] op_sel:[0,1,0]
	v_pk_add_f32 v[248:249], v[248:249], v[250:251]
	v_pk_add_f32 v[252:253], v[252:253], v[198:199]
	v_pk_add_f32 v[248:249], v[248:249], v[252:253]
	v_pk_fma_f32 v[248:249], v[106:107], v[2:3], v[248:249]
	v_pk_fma_f32 v[106:107], v[106:107], v[60:61], v[248:249] op_sel:[1,0,0] op_sel_hi:[0,1,1] neg_hi:[0,1,0]
	v_cvt_pk_bf16_f32 v140, v107, v107
	ds_write_b16 v42, v140 offset:2448
	v_cvt_pk_bf16_f32 v141, v106, v106
	ds_write_b16 v42, v141 offset:2576
	v_readlane_b32 s54, v176, 10
	v_readlane_b32 s55, v177, 10
	v_readlane_b32 s56, v178, 10
	v_readlane_b32 s57, v179, 10
	v_readlane_b32 s58, v180, 10
	v_readlane_b32 s59, v181, 10
	v_readlane_b32 s60, v182, 10
	v_readlane_b32 s61, v183, 10
	v_readlane_b32 s62, v184, 10
	v_readlane_b32 s63, v185, 10
	v_readlane_b32 s64, v186, 10
	v_readlane_b32 s65, v187, 10
	v_readlane_b32 s78, v188, 10
	v_readlane_b32 s79, v189, 10
	v_readlane_b32 s80, v190, 10
	v_readlane_b32 s81, v191, 10
	v_pk_mul_f32 v[248:249], v[216:217], s[54:55] op_sel_hi:[1,0]
	v_pk_mul_f32 v[250:251], v[218:219], s[54:55] op_sel:[0,1]
	v_pk_mul_f32 v[252:253], v[220:221], s[56:57] op_sel_hi:[1,0]
	v_pk_mul_f32 v[198:199], v[222:223], s[56:57] op_sel:[0,1]
	v_pk_fma_f32 v[248:249], v[224:225], s[58:59], v[248:249] op_sel_hi:[1,0,1]
	v_pk_fma_f32 v[250:251], v[226:227], s[58:59], v[250:251] op_sel:[0,1,0]
	v_pk_fma_f32 v[252:253], v[228:229], s[60:61], v[252:253] op_sel_hi:[1,0,1]
	v_pk_fma_f32 v[198:199], v[230:231], s[60:61], v[198:199] op_sel:[0,1,0]
	v_pk_fma_f32 v[248:249], v[232:233], s[62:63], v[248:249] op_sel_hi:[1,0,1]
	v_pk_fma_f32 v[250:251], v[234:235], s[62:63], v[250:251] op_sel:[0,1,0]
	v_pk_fma_f32 v[252:253], v[236:237], s[64:65], v[252:253] op_sel_hi:[1,0,1]
	v_pk_fma_f32 v[198:199], v[238:239], s[64:65], v[198:199] op_sel:[0,1,0]
	v_pk_fma_f32 v[248:249], v[240:241], s[78:79], v[248:249] op_sel_hi:[1,0,1]
	v_pk_fma_f32 v[250:251], v[242:243], s[78:79], v[250:251] op_sel:[0,1,0]
	v_pk_fma_f32 v[252:253], v[244:245], s[80:81], v[252:253] op_sel_hi:[1,0,1]
	v_pk_fma_f32 v[198:199], v[246:247], s[80:81], v[198:199] op_sel:[0,1,0]
	v_pk_add_f32 v[248:249], v[248:249], v[250:251]
	v_pk_add_f32 v[252:253], v[252:253], v[198:199]
	v_pk_add_f32 v[248:249], v[248:249], v[252:253]
	v_pk_fma_f32 v[248:249], v[106:107], v[2:3], v[248:249]
	v_pk_fma_f32 v[106:107], v[106:107], v[60:61], v[248:249] op_sel:[1,0,0] op_sel_hi:[0,1,1] neg_hi:[0,1,0]
	v_cvt_pk_bf16_f32 v140, v107, v107
	ds_write_b16 v42, v140 offset:2720
	v_cvt_pk_bf16_f32 v141, v106, v106
	ds_write_b16 v42, v141 offset:2848
	v_readlane_b32 s54, v176, 11
	v_readlane_b32 s55, v177, 11
	v_readlane_b32 s56, v178, 11
	v_readlane_b32 s57, v179, 11
	v_readlane_b32 s58, v180, 11
	v_readlane_b32 s59, v181, 11
	v_readlane_b32 s60, v182, 11
	v_readlane_b32 s61, v183, 11
	v_readlane_b32 s62, v184, 11
	v_readlane_b32 s63, v185, 11
	v_readlane_b32 s64, v186, 11
	v_readlane_b32 s65, v187, 11
	v_readlane_b32 s78, v188, 11
	v_readlane_b32 s79, v189, 11
	v_readlane_b32 s80, v190, 11
	v_readlane_b32 s81, v191, 11
	v_pk_mul_f32 v[248:249], v[216:217], s[54:55] op_sel_hi:[1,0]
	v_pk_mul_f32 v[250:251], v[218:219], s[54:55] op_sel:[0,1]
	v_pk_mul_f32 v[252:253], v[220:221], s[56:57] op_sel_hi:[1,0]
	v_pk_mul_f32 v[198:199], v[222:223], s[56:57] op_sel:[0,1]
	v_pk_fma_f32 v[248:249], v[224:225], s[58:59], v[248:249] op_sel_hi:[1,0,1]
	v_pk_fma_f32 v[250:251], v[226:227], s[58:59], v[250:251] op_sel:[0,1,0]
	v_pk_fma_f32 v[252:253], v[228:229], s[60:61], v[252:253] op_sel_hi:[1,0,1]
	v_pk_fma_f32 v[198:199], v[230:231], s[60:61], v[198:199] op_sel:[0,1,0]
	v_pk_fma_f32 v[248:249], v[232:233], s[62:63], v[248:249] op_sel_hi:[1,0,1]
	v_pk_fma_f32 v[250:251], v[234:235], s[62:63], v[250:251] op_sel:[0,1,0]
	v_pk_fma_f32 v[252:253], v[236:237], s[64:65], v[252:253] op_sel_hi:[1,0,1]
	v_pk_fma_f32 v[198:199], v[238:239], s[64:65], v[198:199] op_sel:[0,1,0]
	v_pk_fma_f32 v[248:249], v[240:241], s[78:79], v[248:249] op_sel_hi:[1,0,1]
	v_pk_fma_f32 v[250:251], v[242:243], s[78:79], v[250:251] op_sel:[0,1,0]
	v_pk_fma_f32 v[252:253], v[244:245], s[80:81], v[252:253] op_sel_hi:[1,0,1]
	v_pk_fma_f32 v[198:199], v[246:247], s[80:81], v[198:199] op_sel:[0,1,0]
	v_pk_add_f32 v[248:249], v[248:249], v[250:251]
	v_pk_add_f32 v[252:253], v[252:253], v[198:199]
	v_pk_add_f32 v[248:249], v[248:249], v[252:253]
	v_pk_fma_f32 v[248:249], v[106:107], v[2:3], v[248:249]
	v_pk_fma_f32 v[106:107], v[106:107], v[60:61], v[248:249] op_sel:[1,0,0] op_sel_hi:[0,1,1] neg_hi:[0,1,0]
	v_cvt_pk_bf16_f32 v140, v107, v107
	ds_write_b16 v42, v140 offset:2992
	v_cvt_pk_bf16_f32 v141, v106, v106
	ds_write_b16 v42, v141 offset:3120
	v_readlane_b32 s54, v176, 12
	v_readlane_b32 s55, v177, 12
	v_readlane_b32 s56, v178, 12
	v_readlane_b32 s57, v179, 12
	v_readlane_b32 s58, v180, 12
	v_readlane_b32 s59, v181, 12
	v_readlane_b32 s60, v182, 12
	v_readlane_b32 s61, v183, 12
	v_readlane_b32 s62, v184, 12
	v_readlane_b32 s63, v185, 12
	v_readlane_b32 s64, v186, 12
	v_readlane_b32 s65, v187, 12
	v_readlane_b32 s78, v188, 12
	v_readlane_b32 s79, v189, 12
	v_readlane_b32 s80, v190, 12
	v_readlane_b32 s81, v191, 12
	v_pk_mul_f32 v[248:249], v[216:217], s[54:55] op_sel_hi:[1,0]
	v_pk_mul_f32 v[250:251], v[218:219], s[54:55] op_sel:[0,1]
	v_pk_mul_f32 v[252:253], v[220:221], s[56:57] op_sel_hi:[1,0]
	v_pk_mul_f32 v[198:199], v[222:223], s[56:57] op_sel:[0,1]
	v_pk_fma_f32 v[248:249], v[224:225], s[58:59], v[248:249] op_sel_hi:[1,0,1]
	v_pk_fma_f32 v[250:251], v[226:227], s[58:59], v[250:251] op_sel:[0,1,0]
; __device__ __forceinline__ float lo_f(unsigned w) { return __uint_as_float(w << 16); }
; __device__ __forceinline__ float hi_f(unsigned w) { return __uint_as_float(w & 0xffff0000u); }
; __device__ __forceinline__ bf16_t f2bf_(float v) { return (bf16_t)(pk2(v, v) & 0xffffu); }
; __device__ __forceinline__ void s5_item(CPar p, int l, int s, int g, float* wl) {
;     ...
;         for (int i = 0; i < 16; ++i) {
;             float br4[4] = {0.f, 0.f, 0.f, 0.f}, bi4[4] = {0.f, 0.f, 0.f, 0.f};
; #pragma unroll
;             for (int w = 0; w < 8; ++w) { const unsigned word = (unsigned)__builtin_amdgcn_readlane((int)(w < 4 ? ca[w] : cbv[w - 4]), i);
;                 const float u0 = lo_f(word), u1 = hi_f(word);
;                 br4[w & 3] += bbr[2 * w] * u0 + bbr[2 * w + 1] * u1; bi4[w & 3] += bbi[2 * w] * u0 + bbi[2 * w + 1] * u1; }
;             const float bur = (br4[0] + br4[1]) + (br4[2] + br4[3]), bui = (bi4[0] + bi4[1]) + (bi4[2] + bi4[3]);
;             const float nxr = ab_re * xr - ab_im * xi + bur, nxi = ab_re * xi + ab_im * xr + bui; xr = nxr; xi = nxi;
;             Xb[i * LBX + lane] = f2bf_(xr); Xb[i * LBX + 64 + lane] = f2bf_(xi);
	v_pk_fma_f32 v[252:253], v[228:229], s[60:61], v[252:253] op_sel_hi:[1,0,1]
	v_pk_fma_f32 v[198:199], v[230:231], s[60:61], v[198:199] op_sel:[0,1,0]
	v_pk_fma_f32 v[248:249], v[232:233], s[62:63], v[248:249] op_sel_hi:[1,0,1]
	v_pk_fma_f32 v[250:251], v[234:235], s[62:63], v[250:251] op_sel:[0,1,0]
	v_pk_fma_f32 v[252:253], v[236:237], s[64:65], v[252:253] op_sel_hi:[1,0,1]
	v_pk_fma_f32 v[198:199], v[238:239], s[64:65], v[198:199] op_sel:[0,1,0]
	v_pk_fma_f32 v[248:249], v[240:241], s[78:79], v[248:249] op_sel_hi:[1,0,1]
	v_pk_fma_f32 v[250:251], v[242:243], s[78:79], v[250:251] op_sel:[0,1,0]
	v_pk_fma_f32 v[252:253], v[244:245], s[80:81], v[252:253] op_sel_hi:[1,0,1]
	v_pk_fma_f32 v[198:199], v[246:247], s[80:81], v[198:199] op_sel:[0,1,0]
	v_pk_add_f32 v[248:249], v[248:249], v[250:251]
	v_pk_add_f32 v[252:253], v[252:253], v[198:199]
	v_pk_add_f32 v[248:249], v[248:249], v[252:253]
	v_pk_fma_f32 v[248:249], v[106:107], v[2:3], v[248:249]
	v_pk_fma_f32 v[106:107], v[106:107], v[60:61], v[248:249] op_sel:[1,0,0] op_sel_hi:[0,1,1] neg_hi:[0,1,0]
	v_cvt_pk_bf16_f32 v140, v107, v107
	ds_write_b16 v42, v140 offset:3264
	v_cvt_pk_bf16_f32 v141, v106, v106
	ds_write_b16 v42, v141 offset:3392
	v_readlane_b32 s54, v176, 13
	v_readlane_b32 s55, v177, 13
	v_readlane_b32 s56, v178, 13
	v_readlane_b32 s57, v179, 13
	v_readlane_b32 s58, v180, 13
	v_readlane_b32 s59, v181, 13
	v_readlane_b32 s60, v182, 13
	v_readlane_b32 s61, v183, 13
	v_readlane_b32 s62, v184, 13
	v_readlane_b32 s63, v185, 13
	v_readlane_b32 s64, v186, 13
	v_readlane_b32 s65, v187, 13
	v_readlane_b32 s78, v188, 13
	v_readlane_b32 s79, v189, 13
	v_readlane_b32 s80, v190, 13
	v_readlane_b32 s81, v191, 13
	v_pk_mul_f32 v[248:249], v[216:217], s[54:55] op_sel_hi:[1,0]
	v_pk_mul_f32 v[250:251], v[218:219], s[54:55] op_sel:[0,1]
	v_pk_mul_f32 v[252:253], v[220:221], s[56:57] op_sel_hi:[1,0]
	v_pk_mul_f32 v[198:199], v[222:223], s[56:57] op_sel:[0,1]
	v_pk_fma_f32 v[248:249], v[224:225], s[58:59], v[248:249] op_sel_hi:[1,0,1]
	v_pk_fma_f32 v[250:251], v[226:227], s[58:59], v[250:251] op_sel:[0,1,0]
	v_pk_fma_f32 v[252:253], v[228:229], s[60:61], v[252:253] op_sel_hi:[1,0,1]
	v_pk_fma_f32 v[198:199], v[230:231], s[60:61], v[198:199] op_sel:[0,1,0]
	v_pk_fma_f32 v[248:249], v[232:233], s[62:63], v[248:249] op_sel_hi:[1,0,1]
	v_pk_fma_f32 v[250:251], v[234:235], s[62:63], v[250:251] op_sel:[0,1,0]
	v_pk_fma_f32 v[252:253], v[236:237], s[64:65], v[252:253] op_sel_hi:[1,0,1]
	v_pk_fma_f32 v[198:199], v[238:239], s[64:65], v[198:199] op_sel:[0,1,0]
	v_pk_fma_f32 v[248:249], v[240:241], s[78:79], v[248:249] op_sel_hi:[1,0,1]
	v_pk_fma_f32 v[250:251], v[242:243], s[78:79], v[250:251] op_sel:[0,1,0]
	v_pk_fma_f32 v[252:253], v[244:245], s[80:81], v[252:253] op_sel_hi:[1,0,1]
	v_pk_fma_f32 v[198:199], v[246:247], s[80:81], v[198:199] op_sel:[0,1,0]
	v_pk_add_f32 v[248:249], v[248:249], v[250:251]
	v_pk_add_f32 v[252:253], v[252:253], v[198:199]
	v_pk_add_f32 v[248:249], v[248:249], v[252:253]
	v_pk_fma_f32 v[248:249], v[106:107], v[2:3], v[248:249]
	v_pk_fma_f32 v[106:107], v[106:107], v[60:61], v[248:249] op_sel:[1,0,0] op_sel_hi:[0,1,1] neg_hi:[0,1,0]
	v_cvt_pk_bf16_f32 v140, v107, v107
	ds_write_b16 v42, v140 offset:3536
	v_cvt_pk_bf16_f32 v141, v106, v106
	ds_write_b16 v42, v141 offset:3664
	v_readlane_b32 s54, v176, 14
	v_readlane_b32 s55, v177, 14
	v_readlane_b32 s56, v178, 14
	v_readlane_b32 s57, v179, 14
	v_readlane_b32 s58, v180, 14
	v_readlane_b32 s59, v181, 14
	v_readlane_b32 s60, v182, 14
	v_readlane_b32 s61, v183, 14
	v_readlane_b32 s62, v184, 14
	v_readlane_b32 s63, v185, 14
	v_readlane_b32 s64, v186, 14
	v_readlane_b32 s65, v187, 14
	v_readlane_b32 s78, v188, 14
	v_readlane_b32 s79, v189, 14
	v_readlane_b32 s80, v190, 14
	v_readlane_b32 s81, v191, 14
	v_pk_mul_f32 v[248:249], v[216:217], s[54:55] op_sel_hi:[1,0]
	v_pk_mul_f32 v[250:251], v[218:219], s[54:55] op_sel:[0,1]
	v_pk_mul_f32 v[252:253], v[220:221], s[56:57] op_sel_hi:[1,0]
	v_pk_mul_f32 v[198:199], v[222:223], s[56:57] op_sel:[0,1]
	v_pk_fma_f32 v[248:249], v[224:225], s[58:59], v[248:249] op_sel_hi:[1,0,1]
	v_pk_fma_f32 v[250:251], v[226:227], s[58:59], v[250:251] op_sel:[0,1,0]
	v_pk_fma_f32 v[252:253], v[228:229], s[60:61], v[252:253] op_sel_hi:[1,0,1]
	v_pk_fma_f32 v[198:199], v[230:231], s[60:61], v[198:199] op_sel:[0,1,0]
	v_pk_fma_f32 v[248:249], v[232:233], s[62:63], v[248:249] op_sel_hi:[1,0,1]
	v_pk_fma_f32 v[250:251], v[234:235], s[62:63], v[250:251] op_sel:[0,1,0]
	v_pk_fma_f32 v[252:253], v[236:237], s[64:65], v[252:253] op_sel_hi:[1,0,1]
	v_pk_fma_f32 v[198:199], v[238:239], s[64:65], v[198:199] op_sel:[0,1,0]
	v_pk_fma_f32 v[248:249], v[240:241], s[78:79], v[248:249] op_sel_hi:[1,0,1]
	v_pk_fma_f32 v[250:251], v[242:243], s[78:79], v[250:251] op_sel:[0,1,0]
	v_pk_fma_f32 v[252:253], v[244:245], s[80:81], v[252:253] op_sel_hi:[1,0,1]
	v_pk_fma_f32 v[198:199], v[246:247], s[80:81], v[198:199] op_sel:[0,1,0]
	v_pk_add_f32 v[248:249], v[248:249], v[250:251]
	v_pk_add_f32 v[252:253], v[252:253], v[198:199]
	v_pk_add_f32 v[248:249], v[248:249], v[252:253]
	v_pk_fma_f32 v[248:249], v[106:107], v[2:3], v[248:249]
	v_pk_fma_f32 v[106:107], v[106:107], v[60:61], v[248:249] op_sel:[1,0,0] op_sel_hi:[0,1,1] neg_hi:[0,1,0]
	v_cvt_pk_bf16_f32 v140, v107, v107
	ds_write_b16 v42, v140 offset:3808
	v_cvt_pk_bf16_f32 v141, v106, v106
	ds_write_b16 v42, v141 offset:3936
	v_readlane_b32 s54, v176, 15
	v_readlane_b32 s55, v177, 15
; __device__ __forceinline__ float bf2f(bf16_t v) { return __uint_as_float((unsigned)v << 16); }
; __device__ __forceinline__ float lo_f(unsigned w) { return __uint_as_float(w << 16); }
; __device__ __forceinline__ float hi_f(unsigned w) { return __uint_as_float(w & 0xffff0000u); }
; __device__ __forceinline__ float geluf_(float y) { const float a = 0.7978845608f * (y + 0.044715f * y * y * y); const float t = __expf(2.f * a); return 0.5f * y * (2.f - 2.f * __builtin_amdgcn_rcpf(t + 1.f)); }
; __device__ __forceinline__ bf16_t f2bf_(float v) { return (bf16_t)(pk2(v, v) & 0xffffu); }
; __device__ __forceinline__ void s5_item(CPar p, int l, int s, int g, float* wl) {
;     ...
;         for (int i = 0; i < 16; ++i) {
;             float br4[4] = {0.f, 0.f, 0.f, 0.f}, bi4[4] = {0.f, 0.f, 0.f, 0.f};
; #pragma unroll
;             for (int w = 0; w < 8; ++w) { const unsigned word = (unsigned)__builtin_amdgcn_readlane((int)(w < 4 ? ca[w] : cbv[w - 4]), i);
;                 const float u0 = lo_f(word), u1 = hi_f(word);
;                 br4[w & 3] += bbr[2 * w] * u0 + bbr[2 * w + 1] * u1; bi4[w & 3] += bbi[2 * w] * u0 + bbi[2 * w + 1] * u1; }
;             const float bur = (br4[0] + br4[1]) + (br4[2] + br4[3]), bui = (bi4[0] + bi4[1]) + (bi4[2] + bi4[3]);
;             const float nxr = ab_re * xr - ab_im * xi + bur, nxi = ab_re * xi + ab_im * xr + bui; xr = nxr; xi = nxi;
;             Xb[i * LBX + lane] = f2bf_(xr); Xb[i * LBX + 64 + lane] = f2bf_(xi);
;         }
;         __builtin_amdgcn_wave_barrier(); asm volatile("s_waitcnt lgkmcnt(0)" ::: "memory");
;         f32x4 y = {0.f, 0.f, 0.f, 0.f};
; #pragma unroll
;         for (int ks = 0; ks < 4; ++ks) y = __builtin_amdgcn_mfma_f32_16x16x32_bf16(*(const bf16x8*)(Xb + fr * LBX + ks * 32 + fq * 8), cfrag[ks], y, 0, 0, 0);
; #pragma unroll
;         for (int r = 0; r < 4; ++r) { bf16_t* up = U + (size_t)(r0 + fq * 4 + r) * 512 + g * 16 + fr; *up = f2bf_(geluf_(y[r] + dsk * bf2f(*up))); }
;         __builtin_amdgcn_wave_barrier(); asm volatile("s_waitcnt lgkmcnt(0)" ::: "memory");
	v_readlane_b32 s56, v178, 15
	v_readlane_b32 s57, v179, 15
	v_readlane_b32 s58, v180, 15
	v_readlane_b32 s59, v181, 15
	v_readlane_b32 s60, v182, 15
	v_readlane_b32 s61, v183, 15
	v_readlane_b32 s62, v184, 15
	v_readlane_b32 s63, v185, 15
	v_readlane_b32 s64, v186, 15
	v_readlane_b32 s65, v187, 15
	v_readlane_b32 s78, v188, 15
	v_readlane_b32 s79, v189, 15
	v_readlane_b32 s80, v190, 15
	v_readlane_b32 s81, v191, 15
	v_pk_mul_f32 v[248:249], v[216:217], s[54:55] op_sel_hi:[1,0]
	v_pk_mul_f32 v[250:251], v[218:219], s[54:55] op_sel:[0,1]
	v_pk_mul_f32 v[252:253], v[220:221], s[56:57] op_sel_hi:[1,0]
	v_pk_mul_f32 v[198:199], v[222:223], s[56:57] op_sel:[0,1]
	v_pk_fma_f32 v[248:249], v[224:225], s[58:59], v[248:249] op_sel_hi:[1,0,1]
	v_pk_fma_f32 v[250:251], v[226:227], s[58:59], v[250:251] op_sel:[0,1,0]
	v_pk_fma_f32 v[252:253], v[228:229], s[60:61], v[252:253] op_sel_hi:[1,0,1]
	v_pk_fma_f32 v[198:199], v[230:231], s[60:61], v[198:199] op_sel:[0,1,0]
	v_pk_fma_f32 v[248:249], v[232:233], s[62:63], v[248:249] op_sel_hi:[1,0,1]
	v_pk_fma_f32 v[250:251], v[234:235], s[62:63], v[250:251] op_sel:[0,1,0]
	v_pk_fma_f32 v[252:253], v[236:237], s[64:65], v[252:253] op_sel_hi:[1,0,1]
	v_pk_fma_f32 v[198:199], v[238:239], s[64:65], v[198:199] op_sel:[0,1,0]
	v_pk_fma_f32 v[248:249], v[240:241], s[78:79], v[248:249] op_sel_hi:[1,0,1]
	v_pk_fma_f32 v[250:251], v[242:243], s[78:79], v[250:251] op_sel:[0,1,0]
	v_pk_fma_f32 v[252:253], v[244:245], s[80:81], v[252:253] op_sel_hi:[1,0,1]
	v_pk_fma_f32 v[198:199], v[246:247], s[80:81], v[198:199] op_sel:[0,1,0]
	v_pk_add_f32 v[248:249], v[248:249], v[250:251]
	v_pk_add_f32 v[252:253], v[252:253], v[198:199]
	v_pk_add_f32 v[248:249], v[248:249], v[252:253]
	v_pk_fma_f32 v[248:249], v[106:107], v[2:3], v[248:249]
	v_pk_fma_f32 v[106:107], v[106:107], v[60:61], v[248:249] op_sel:[1,0,0] op_sel_hi:[0,1,1] neg_hi:[0,1,0]
	v_cvt_pk_bf16_f32 v140, v107, v107
	ds_write_b16 v42, v140 offset:4080
	v_cvt_pk_bf16_f32 v141, v106, v106
	ds_write_b16 v42, v141 offset:4208
	s_add_i32 s12, s12, 1
	s_add_i32 s11, s11, 16
	s_cmpk_eq_i32 s12, 0x81
	s_waitcnt lgkmcnt(0)
	ds_read_b128 v[20:23], v1
	ds_read_b128 v[24:27], v1 offset:64
	s_waitcnt lgkmcnt(1)
	v_mfma_f32_16x16x32_bf16 v[20:23], v[20:23], v[4:7], 0
	s_waitcnt lgkmcnt(0)
	v_mfma_f32_16x16x32_bf16 v[20:23], v[24:27], v[8:11], v[20:23]
	ds_read_b128 v[24:27], v1 offset:128
	ds_read_b128 v[110:113], v1 offset:192
	s_waitcnt lgkmcnt(1)
	v_mfma_f32_16x16x32_bf16 v[20:23], v[24:27], v[12:15], v[20:23]
	v_or_b32_e32 v24, s13, v40
	v_ashrrev_i32_e32 v25, 31, v24
	v_lshlrev_b64 v[26:27], 10, v[24:25]
	v_lshl_add_u64 v[26:27], v[104:105], 0, v[26:27]
	s_waitcnt lgkmcnt(0)
	v_mfma_f32_16x16x32_bf16 v[20:23], v[110:113], v[16:19], v[20:23]
	v_or_b32_e32 v110, 1, v24
	v_ashrrev_i32_e32 v111, 31, v110
	v_lshlrev_b64 v[110:111], 10, v[110:111]
	v_lshl_add_u64 v[110:111], v[104:105], 0, v[110:111]
	s_waitcnt vmcnt(0)
	v_lshlrev_b32_e32 v25, 16, v194
	s_nop 1
	v_fma_f32 v20, v109, v25, v20
	v_mul_f32_e32 v25, 0x3d372713, v20
	v_mul_f32_e32 v25, v20, v25
	v_fma_f32 v25, v20, v25, v20
	v_mul_f32_e32 v25, 0x3f4c422a, v25
	v_add_f32_e32 v25, v25, v25
	v_mul_f32_e32 v25, 0x3fb8aa3b, v25
	v_exp_f32_e32 v25, v25
	v_mul_f32_e32 v20, 0.5, v20
	v_add_f32_e32 v25, 1.0, v25
	v_rcp_f32_e32 v25, v25
	s_nop 0
	v_fma_f32 v25, v25, -2.0, 2.0
	v_mul_f32_e32 v20, v20, v25
	v_cvt_pk_bf16_f32 v20, v20, v20
	v_lshlrev_b32_e32 v25, 16, v195
	v_fma_f32 v21, v109, v25, v21
	v_mul_f32_e32 v25, 0x3d372713, v21
	v_mul_f32_e32 v25, v21, v25
	v_fma_f32 v25, v21, v25, v21
	v_mul_f32_e32 v25, 0x3f4c422a, v25
	v_add_f32_e32 v25, v25, v25
	v_mul_f32_e32 v25, 0x3fb8aa3b, v25
	v_exp_f32_e32 v25, v25
	global_store_short v[26:27], v20, off
	v_mul_f32_e32 v20, 0.5, v21
	v_add_f32_e32 v25, 1.0, v25
	v_rcp_f32_e32 v25, v25
	s_nop 0
	v_fma_f32 v21, v25, -2.0, 2.0
	v_mul_f32_e32 v20, v20, v21
	v_cvt_pk_bf16_f32 v25, v20, v20
	v_or_b32_e32 v20, 2, v24
	v_ashrrev_i32_e32 v21, 31, v20
	v_lshlrev_b64 v[20:21], 10, v[20:21]
	v_lshl_add_u64 v[20:21], v[104:105], 0, v[20:21]
	v_or_b32_e32 v24, 3, v24
	global_store_short v[110:111], v25, off
	v_lshlrev_b32_e32 v26, 16, v196
	v_fma_f32 v22, v109, v26, v22
	v_mul_f32_e32 v26, 0x3d372713, v22
	v_mul_f32_e32 v26, v22, v26
	v_fma_f32 v26, v22, v26, v22
	v_mul_f32_e32 v26, 0x3f4c422a, v26
	v_add_f32_e32 v26, v26, v26
	v_mul_f32_e32 v26, 0x3fb8aa3b, v26
	v_exp_f32_e32 v26, v26
	v_mul_f32_e32 v22, 0.5, v22
	v_add_f32_e32 v26, 1.0, v26
	v_rcp_f32_e32 v26, v26
	s_nop 0
	v_fma_f32 v25, v26, -2.0, 2.0
	v_mul_f32_e32 v22, v22, v25
	v_ashrrev_i32_e32 v25, 31, v24
	v_lshlrev_b64 v[24:25], 10, v[24:25]
	v_lshl_add_u64 v[24:25], v[104:105], 0, v[24:25]
	v_cvt_pk_bf16_f32 v22, v22, v22
	v_lshlrev_b32_e32 v26, 16, v197
	v_fmac_f32_e32 v23, v109, v26
	v_mul_f32_e32 v26, 0x3d372713, v23
	v_mul_f32_e32 v26, v23, v26
	v_fma_f32 v26, v23, v26, v23
	v_mul_f32_e32 v26, 0x3f4c422a, v26
	v_add_f32_e32 v26, v26, v26
	v_mul_f32_e32 v26, 0x3fb8aa3b, v26
	v_exp_f32_e32 v26, v26
	global_store_short v[20:21], v22, off
	v_mul_f32_e32 v20, 0.5, v23
	v_add_f32_e32 v26, 1.0, v26
	v_rcp_f32_e32 v26, v26
	s_nop 0
	v_fma_f32 v21, v26, -2.0, 2.0
	v_mul_f32_e32 v20, v20, v21
	v_cvt_pk_bf16_f32 v20, v20, v20
	global_store_short v[24:25], v20, off
	s_waitcnt lgkmcnt(0)
	v_mov_b64_e32 v[24:25], v[32:33]
	v_mov_b64_e32 v[20:21], v[28:29]
	v_mov_b64_e32 v[26:27], v[34:35]
	v_mov_b64_e32 v[22:23], v[30:31]
	s_cbranch_scc1 .LBB0_668

; __device__ __forceinline__ float dot2bf(unsigned a, unsigned b, float c) { return __builtin_amdgcn_fdot2_f32_bf16(__builtin_bit_cast(bf2_t, a), __builtin_bit_cast(bf2_t, b), c, false); }
; __device__ __forceinline__ void attn_item(CPar p, int l, int item, float* wl) {
;     ...
;         for (int m = 0; m < npair; ++m) { const int j0 = jt - 2 * m, j1 = j0 - 1;
;             float z0 = 0.f, z1 = 0.f;
; #pragma unroll
;             for (int d8 = 0; d8 < 8; ++d8) { const u32x4 k0 = *(const u32x4*)(Kt + (2 * m) * 32 + d8 * 4), k1 = *(const u32x4*)(Kt + (2 * m + 1) * 32 + d8 * 4);
; #pragma unroll
;                 for (int c = 0; c < 4; ++c) { z0 = dot2bf(q[d8 * 4 + c], k0[c], z0); z1 = dot2bf(q[d8 * 4 + c], k1[c], z1); } }
;             const bool v0 = active && (j0 < nh + i), v1 = active && (j1 >= 0) && (j1 < nh + i);
.LBB0_771:
	v_mov_b32_e32 v2, s9
	ds_read_b128 v[226:229], v2
	ds_read_b128 v[230:233], v2 offset:128
	ds_read_b128 v[234:237], v2 offset:16
	ds_read_b128 v[238:241], v2 offset:144
	ds_read_b128 v[242:245], v2 offset:32
	ds_read_b128 v[246:249], v2 offset:160
	ds_read_b128 v[250:253], v2 offset:48
	v_mov_b32_e32 v79, 0
	v_mov_b32_e32 v3, 0
	s_waitcnt lgkmcnt(6)
	v_dot2c_f32_bf16_e32 v3, v80, v226
	v_dot2c_f32_bf16_e32 v3, v81, v227
	v_dot2c_f32_bf16_e32 v3, v82, v228
	v_dot2c_f32_bf16_e32 v3, v83, v229
	ds_read_b128 v[226:229], v2 offset:176
	s_waitcnt lgkmcnt(6)
	v_dot2c_f32_bf16_e32 v79, v80, v230
	v_dot2c_f32_bf16_e32 v79, v81, v231
	v_dot2c_f32_bf16_e32 v79, v82, v232
	v_dot2c_f32_bf16_e32 v79, v83, v233
	ds_read_b128 v[230:233], v2 offset:64
	s_waitcnt lgkmcnt(6)
	v_dot2c_f32_bf16_e32 v3, v84, v234
	v_dot2c_f32_bf16_e32 v3, v85, v235
	v_dot2c_f32_bf16_e32 v3, v86, v236
	v_dot2c_f32_bf16_e32 v3, v87, v237
	ds_read_b128 v[234:237], v2 offset:192
	s_waitcnt lgkmcnt(6)
	v_dot2c_f32_bf16_e32 v79, v84, v238
	v_dot2c_f32_bf16_e32 v79, v85, v239
	v_dot2c_f32_bf16_e32 v79, v86, v240
	v_dot2c_f32_bf16_e32 v79, v87, v241
	ds_read_b128 v[238:241], v2 offset:80
	s_waitcnt lgkmcnt(6)
	v_dot2c_f32_bf16_e32 v3, v88, v242
	v_dot2c_f32_bf16_e32 v3, v89, v243
	v_dot2c_f32_bf16_e32 v3, v90, v244
	v_dot2c_f32_bf16_e32 v3, v91, v245
	ds_read_b128 v[242:245], v2 offset:208
	s_waitcnt lgkmcnt(6)
	v_dot2c_f32_bf16_e32 v79, v88, v246
	v_dot2c_f32_bf16_e32 v79, v89, v247
	v_dot2c_f32_bf16_e32 v79, v90, v248
	v_dot2c_f32_bf16_e32 v79, v91, v249
	ds_read_b128 v[246:249], v2 offset:96
	s_waitcnt lgkmcnt(6)
	v_dot2c_f32_bf16_e32 v3, v92, v250
	v_dot2c_f32_bf16_e32 v3, v93, v251
	v_dot2c_f32_bf16_e32 v3, v94, v252
	v_dot2c_f32_bf16_e32 v3, v95, v253
	ds_read_b128 v[250:253], v2 offset:224
	s_waitcnt lgkmcnt(6)
	v_dot2c_f32_bf16_e32 v79, v92, v226
	v_dot2c_f32_bf16_e32 v79, v93, v227
	v_dot2c_f32_bf16_e32 v79, v94, v228
	v_dot2c_f32_bf16_e32 v79, v95, v229
	ds_read_b128 v[226:229], v2 offset:112
	s_waitcnt lgkmcnt(6)
	v_dot2c_f32_bf16_e32 v3, v96, v230
	v_dot2c_f32_bf16_e32 v3, v97, v231
	v_dot2c_f32_bf16_e32 v3, v98, v232
	v_dot2c_f32_bf16_e32 v3, v99, v233
	ds_read_b128 v[230:233], v2 offset:240
	v_cmp_lt_i32_e32 vcc, s1, v184
	s_and_b64 vcc, s[40:41], vcc
	s_cmp_gt_i32 s1, 0
	s_waitcnt lgkmcnt(6)
	v_dot2c_f32_bf16_e32 v79, v96, v234
	v_dot2c_f32_bf16_e32 v79, v97, v235
	v_dot2c_f32_bf16_e32 v79, v98, v236
	v_dot2c_f32_bf16_e32 v79, v99, v237
	ds_read_b128 v[234:237], v2 offset:4096
	s_waitcnt lgkmcnt(6)
	v_dot2c_f32_bf16_e32 v3, v100, v238
	v_dot2c_f32_bf16_e32 v3, v101, v239
	v_dot2c_f32_bf16_e32 v3, v102, v240
	v_dot2c_f32_bf16_e32 v3, v103, v241
	ds_read_b128 v[238:241], v2 offset:4112
	s_cselect_b64 s[6:7], -1, 0
	s_and_b64 s[6:7], s[40:41], s[6:7]
	v_cmp_le_i32_e64 s[44:45], s1, v184
	s_waitcnt lgkmcnt(6)
	v_dot2c_f32_bf16_e32 v79, v100, v242
	v_dot2c_f32_bf16_e32 v79, v101, v243
	v_dot2c_f32_bf16_e32 v79, v102, v244
	v_dot2c_f32_bf16_e32 v79, v103, v245
	ds_read_b128 v[242:245], v2 offset:4128
	s_waitcnt lgkmcnt(6)
	v_dot2c_f32_bf16_e32 v3, v104, v246
	v_dot2c_f32_bf16_e32 v3, v105, v247
	v_dot2c_f32_bf16_e32 v3, v106, v248
	v_dot2c_f32_bf16_e32 v3, v107, v249
	ds_read_b128 v[246:249], v2 offset:4144
	s_and_b64 s[44:45], s[6:7], s[44:45]
	s_addk_i32 s9, 0x100
	s_add_i32 s1, s1, -2
	s_waitcnt lgkmcnt(6)
	v_dot2c_f32_bf16_e32 v79, v104, v250
	v_dot2c_f32_bf16_e32 v79, v105, v251
	v_dot2c_f32_bf16_e32 v79, v106, v252
	v_dot2c_f32_bf16_e32 v79, v107, v253
	ds_read_b128 v[250:253], v2 offset:4160
	s_waitcnt lgkmcnt(6)
	v_dot2c_f32_bf16_e32 v3, v108, v226
	v_dot2c_f32_bf16_e32 v3, v109, v227
	v_dot2c_f32_bf16_e32 v3, v110, v228
	v_dot2c_f32_bf16_e32 v3, v111, v229
	ds_read_b128 v[226:229], v2 offset:4176
	s_waitcnt lgkmcnt(6)
; __device__ __forceinline__ unsigned pk2(float lo, float hi) { unsigned r; asm volatile("v_cvt_pk_bf16_f32 %0, %1, %2" : "=v"(r) : "v"(lo), "v"(hi)); return r; }
; __device__ __forceinline__ float dot2bf(unsigned a, unsigned b, float c) { return __builtin_amdgcn_fdot2_f32_bf16(__builtin_bit_cast(bf2_t, a), __builtin_bit_cast(bf2_t, b), c, false); }
; __device__ __forceinline__ void attn_item(CPar p, int l, int item, float* wl) {
;     ...
;             const bool v0 = active && (j0 < nh + i), v1 = active && (j1 >= 0) && (j1 < nh + i);
;             const float e0 = __expf(-z0), ls0 = -__logf(1.f + e0);
;             const float w0 = v0 ? __expf(ls0 + run) : 0.f; run += v0 ? (ls0 - z0) : 0.f;
;             const float e1 = __expf(-z1), ls1 = -__logf(1.f + e1);
;             const float w1 = v1 ? __expf(ls1 + run) : 0.f; run += v1 ? (ls1 - z1) : 0.f;
;             const unsigned wp = pk2(w0, w1);
; #pragma unroll
;             for (int d4 = 0; d4 < 16; ++d4) { const u32x4 vv = *(const u32x4*)(Vp + m * 64 + d4 * 4);
; #pragma unroll
;                 for (int c = 0; c < 4; ++c) o[d4 * 4 + c] = dot2bf(wp, vv[c], o[d4 * 4 + c]); } }
	v_dot2c_f32_bf16_e32 v79, v108, v230
	v_dot2c_f32_bf16_e32 v79, v109, v231
	v_dot2c_f32_bf16_e32 v79, v110, v232
	v_dot2c_f32_bf16_e32 v79, v111, v233
	ds_read_b128 v[230:233], v2 offset:4192
	v_mul_f32_e32 v212, 0xbfb8aa3b, v3
	v_exp_f32_e32 v212, v212
	s_nop 0
	v_add_f32_e32 v212, 1.0, v212
	v_cmp_gt_f32_e64 s[46:47], s38, v212
	s_nop 1
	v_cndmask_b32_e64 v213, 0, 32, s[46:47]
	v_ldexp_f32 v212, v212, v213
	v_log_f32_e32 v212, v212
	s_nop 0
	v_mul_f32_e32 v213, 0x3f317217, v212
	v_fma_f32 v213, v212, s90, -v213
	v_fmac_f32_e32 v213, 0x3377d1cf, v212
	v_fmac_f32_e32 v213, 0x3f317217, v212
	v_cmp_lt_f32_e64 s[48:49], |v212|, s23
	s_nop 1
	v_cndmask_b32_e64 v212, v212, v213, s[48:49]
	v_cndmask_b32_e64 v213, 0, v211, s[46:47]
	v_sub_f32_e32 v212, v212, v213
	v_sub_f32_e32 v213, v224, v212
	v_sub_f32_e64 v3, -v212, v3
	v_mul_f32_e32 v212, 0xbfb8aa3b, v79
	v_mul_f32_e32 v213, 0x3fb8aa3b, v213
	v_exp_f32_e32 v212, v212
	v_exp_f32_e32 v213, v213
	v_cndmask_b32_e32 v3, 0, v3, vcc
	v_add_f32_e32 v3, v224, v3
	v_add_f32_e32 v212, 1.0, v212
	v_cndmask_b32_e32 v213, 0, v213, vcc
	v_cmp_gt_f32_e32 vcc, s38, v212
	s_nop 1
	v_cndmask_b32_e64 v224, 0, 32, vcc
	v_ldexp_f32 v212, v212, v224
	v_log_f32_e32 v212, v212
	s_nop 0
	v_mul_f32_e32 v224, 0x3f317217, v212
	v_fma_f32 v224, v212, s90, -v224
	v_fmac_f32_e32 v224, 0x3377d1cf, v212
	v_fmac_f32_e32 v224, 0x3f317217, v212
	v_cmp_lt_f32_e64 s[46:47], |v212|, s23
	s_nop 1
	v_cndmask_b32_e64 v212, v212, v224, s[46:47]
	v_cndmask_b32_e32 v224, 0, v211, vcc
	v_sub_f32_e32 v212, v212, v224
	v_sub_f32_e32 v224, v3, v212
	v_mul_f32_e32 v224, 0x3fb8aa3b, v224
	v_exp_f32_e32 v224, v224
	v_sub_f32_e64 v79, -v212, v79
	v_cndmask_b32_e64 v79, 0, v79, s[44:45]
	v_add_co_u32_e32 v1, vcc, 1, v1
	v_cndmask_b32_e64 v224, 0, v224, s[44:45]
	v_cvt_pk_bf16_f32 v212, v213, v224
	s_and_b64 vcc, exec, vcc
	s_waitcnt lgkmcnt(6)
	v_dot2c_f32_bf16_e32 v223, v212, v234
	v_dot2c_f32_bf16_e32 v222, v212, v235
	v_dot2c_f32_bf16_e32 v221, v212, v236
	v_dot2c_f32_bf16_e32 v220, v212, v237
	ds_read_b128 v[234:237], v2 offset:4208
	s_waitcnt lgkmcnt(6)
	v_dot2c_f32_bf16_e32 v219, v212, v238
	v_dot2c_f32_bf16_e32 v218, v212, v239
	v_dot2c_f32_bf16_e32 v217, v212, v240
	v_dot2c_f32_bf16_e32 v216, v212, v241
	ds_read_b128 v[238:241], v2 offset:4224
	s_waitcnt lgkmcnt(6)
	v_dot2c_f32_bf16_e32 v199, v212, v242
	v_dot2c_f32_bf16_e32 v198, v212, v243
	v_dot2c_f32_bf16_e32 v197, v212, v244
	v_dot2c_f32_bf16_e32 v196, v212, v245
	ds_read_b128 v[242:245], v2 offset:4240
	s_waitcnt lgkmcnt(6)
	v_dot2c_f32_bf16_e32 v195, v212, v246
	v_dot2c_f32_bf16_e32 v194, v212, v247
	v_dot2c_f32_bf16_e32 v193, v212, v248
	v_dot2c_f32_bf16_e32 v192, v212, v249
	ds_read_b128 v[246:249], v2 offset:4256
	s_waitcnt lgkmcnt(6)
	v_dot2c_f32_bf16_e32 v191, v212, v250
	v_dot2c_f32_bf16_e32 v190, v212, v251
	v_dot2c_f32_bf16_e32 v188, v212, v252
	v_dot2c_f32_bf16_e32 v187, v212, v253
	ds_read_b128 v[250:253], v2 offset:4272
	s_waitcnt lgkmcnt(6)
	v_dot2c_f32_bf16_e32 v185, v212, v226
	v_dot2c_f32_bf16_e32 v183, v212, v227
	v_dot2c_f32_bf16_e32 v182, v212, v228
	v_dot2c_f32_bf16_e32 v181, v212, v229
	ds_read_b128 v[226:229], v2 offset:4288
	s_waitcnt lgkmcnt(6)
	v_dot2c_f32_bf16_e32 v180, v212, v230
	v_dot2c_f32_bf16_e32 v179, v212, v231
	v_dot2c_f32_bf16_e32 v178, v212, v232
	v_dot2c_f32_bf16_e32 v177, v212, v233
	ds_read_b128 v[230:233], v2 offset:4304
	s_waitcnt lgkmcnt(6)
	v_dot2c_f32_bf16_e32 v176, v212, v234
	v_dot2c_f32_bf16_e32 v171, v212, v235
	v_dot2c_f32_bf16_e32 v158, v212, v236
	v_dot2c_f32_bf16_e32 v157, v212, v237
	ds_read_b128 v[234:237], v2 offset:4320
	s_waitcnt lgkmcnt(6)
	v_dot2c_f32_bf16_e32 v155, v212, v238
	v_dot2c_f32_bf16_e32 v154, v212, v239
	v_dot2c_f32_bf16_e32 v153, v212, v240
	v_dot2c_f32_bf16_e32 v152, v212, v241
	ds_read_b128 v[238:241], v2 offset:4336
	s_waitcnt lgkmcnt(6)
	v_dot2c_f32_bf16_e32 v151, v212, v242
	v_dot2c_f32_bf16_e32 v150, v212, v243
	v_dot2c_f32_bf16_e32 v149, v212, v244
	v_dot2c_f32_bf16_e32 v148, v212, v245
	s_waitcnt lgkmcnt(5)
	v_dot2c_f32_bf16_e32 v147, v212, v246
	v_dot2c_f32_bf16_e32 v146, v212, v247
	v_dot2c_f32_bf16_e32 v145, v212, v248
	v_dot2c_f32_bf16_e32 v144, v212, v249
	s_waitcnt lgkmcnt(4)
	v_dot2c_f32_bf16_e32 v143, v212, v250
	v_dot2c_f32_bf16_e32 v142, v212, v251
	v_dot2c_f32_bf16_e32 v141, v212, v252
	v_dot2c_f32_bf16_e32 v140, v212, v253
	s_waitcnt lgkmcnt(3)
	v_dot2c_f32_bf16_e32 v139, v212, v226
	v_dot2c_f32_bf16_e32 v138, v212, v227
	v_dot2c_f32_bf16_e32 v137, v212, v228
	v_dot2c_f32_bf16_e32 v136, v212, v229
	s_waitcnt lgkmcnt(2)
	v_dot2c_f32_bf16_e32 v135, v212, v230
	v_dot2c_f32_bf16_e32 v134, v212, v231
	v_dot2c_f32_bf16_e32 v133, v212, v232
	v_dot2c_f32_bf16_e32 v132, v212, v233
	s_waitcnt lgkmcnt(1)
	v_dot2c_f32_bf16_e32 v131, v212, v234
	v_dot2c_f32_bf16_e32 v130, v212, v235
	v_dot2c_f32_bf16_e32 v129, v212, v236
	v_dot2c_f32_bf16_e32 v128, v212, v237
	s_waitcnt lgkmcnt(0)
	v_dot2c_f32_bf16_e32 v127, v212, v238
	v_dot2c_f32_bf16_e32 v126, v212, v239
	v_dot2c_f32_bf16_e32 v125, v212, v240
	v_dot2c_f32_bf16_e32 v124, v212, v241
	v_add_f32_e32 v224, v3, v79
	s_cbranch_vccz .LBB0_771
	s_mov_b32 s1, 0xc2480000
	v_cmp_gt_f32_e32 vcc, s1, v224
	s_or_b64 s[6:7], s[42:43], vcc
	s_waitcnt lgkmcnt(0)
	v_cndmask_b32_e64 v1, 0, 1, s[6:7]
	v_cmp_ne_u32_e32 vcc, 0, v1
	s_cmp_eq_u64 vcc, exec
	s_cselect_b64 s[28:29], -1, 0
	s_and_b64 vcc, exec, s[28:29]
	s_cbranch_vccz .LBB0_774
	s_branch .LBB0_775
